# speedup vs baseline: 1.0056x; 1.0043x over previous
; template <class T> __device__ __forceinline__ void run_epilogue(const TileDesc& d, f32x4 (&acc)[8][4], const unsigned (&xcr)[32], int wr, int wc, int fr, int fq) {
;   switch (d.kind) {
;     case EPI_BF16:   EpiBf16{(bf16*)d.C, d.ldc}(acc, wr, wc, fr, fq); break;
;     case EPI_RELU2:  EpiRelu2{(bf16*)d.C, d.ldc}(acc, wr, wc, fr, fq); break;
;     case EPI_SCALE:  EpiScale{(bf16*)d.C, d.ldc, (const float*)d.e1}(acc, wr, wc, fr, fq); break;
;     case EPI_F32:    EpiF32{(float*)d.C, d.ldc}(acc, wr, wc, fr, fq); break;
;     case EPI_KV:     EpiKV{(bf16*)d.C, (bf16*)d.e0, d.ival}(acc, wr, wc, fr, fq); break;
;     case EPI_SOFTMAX: EpiSoftmax{(bf16*)d.C}(acc, wr, wc, fr, fq); break;
;     case EPI_SIGM:   EpiSigm{(unsigned char*)d.C, d.ldc}(acc, wr, wc, fr, fq); break;
.LBB0_394:
	s_mov_b64 s[16:17], -1
	s_mov_b64 s[4:5], 0
	s_cmp_lt_i32 s90, 3
	s_mov_b64 s[34:35], 0
	s_cbranch_scc1 .LBB0_445
	s_cmp_gt_i32 s90, 4
	s_cbranch_scc0 .LBB0_435
	s_cmp_gt_i32 s90, 5
	s_cbranch_scc0 .LBB0_400
	s_cmp_eq_u32 s90, 6
	s_mov_b64 s[34:35], -1
	s_cbranch_scc0 .LBB0_399
	s_mov_b32 s100, 0xbfb8aa3b
	s_mov_b32 s101, 0x437f0000
	v_mov_b32_e32 v147, v195
	v_mov_b32_e32 v148, v193
	v_mov_b32_e32 v149, v194
	v_mov_b32_e32 v144, v165
	v_mul_f32_e32 v152, s100, v123
	v_lshlrev_b32_e32 v145, 6, v147
	v_lshlrev_b32_e32 v150, 2, v147
	v_lshlrev_b32_e32 v147, 15, v149
	v_lshlrev_b32_e32 v146, 4, v148
	v_lshl_add_u32 v147, v148, 2, v147
	v_lshlrev_b32_e32 v148, 8, v144
	v_add3_u32 v151, v147, v148, s89
	v_mul_f32_e32 v147, s100, v124
	v_mul_f32_e32 v148, s100, v125
	v_exp_f32_e32 v147, v147
	v_exp_f32_e32 v148, v148
	v_lshl_add_u32 v145, v149, 8, v145
	v_mul_f32_e32 v149, s100, v127
	v_add_f32_e32 v147, 1.0, v147
	v_add_f32_e32 v148, 1.0, v148
	v_rcp_f32_e32 v147, v147
	v_rcp_f32_e32 v148, v148
	v_exp_f32_e32 v149, v149
	v_exp_f32_e32 v152, v152
	v_mul_f32_e32 v147, s101, v147
	v_mul_f32_e32 v148, s101, v148
	v_cvt_rpi_i32_f32_e32 v147, v147
	v_cvt_rpi_i32_f32_e32 v148, v148
	v_add_f32_e32 v149, 1.0, v149
	v_rcp_f32_e32 v149, v149
	v_lshl_or_b32 v147, v148, 8, v147
	v_mul_f32_e32 v148, s100, v126
	v_exp_f32_e32 v148, v148
	v_mul_f32_e32 v149, s101, v149
	v_cvt_rpi_i32_f32_e32 v149, v149
	v_add_f32_e32 v148, 1.0, v148
	v_rcp_f32_e32 v148, v148
	v_add_f32_e32 v152, 1.0, v152
	v_min_u32_sdwa v149, v149, s81 dst_sel:BYTE_3 dst_unused:UNUSED_PAD src0_sel:DWORD src1_sel:DWORD
	v_rcp_f32_e32 v152, v152
	v_mul_f32_e32 v148, s101, v148
	v_cvt_rpi_i32_f32_e32 v148, v148
	v_mul_f32_e32 v152, s101, v152
	v_cvt_rpi_i32_f32_e32 v152, v152
	v_min_u32_sdwa v148, v148, s81 dst_sel:WORD_1 dst_unused:UNUSED_PAD src0_sel:DWORD src1_sel:DWORD
	v_mul_f32_e32 v153, s100, v119
	v_or3_b32 v148, v147, v148, v149
	v_xor_b32_e32 v147, v150, v144
	v_lshl_add_u32 v147, v147, 4, v151
	ds_write_b32 v147, v148
	v_mul_f32_e32 v148, s100, v120
	v_mul_f32_e32 v149, s100, v121
	v_exp_f32_e32 v148, v148
	v_exp_f32_e32 v149, v149
	v_min_u32_sdwa v152, v152, s81 dst_sel:BYTE_3 dst_unused:UNUSED_PAD src0_sel:DWORD src1_sel:DWORD
	v_exp_f32_e32 v153, v153
	v_add_f32_e32 v148, 1.0, v148
	v_add_f32_e32 v149, 1.0, v149
	v_rcp_f32_e32 v148, v148
	v_rcp_f32_e32 v149, v149
	v_add_f32_e32 v153, 1.0, v153
	v_rcp_f32_e32 v153, v153
	v_mul_f32_e32 v148, s101, v148
	v_mul_f32_e32 v149, s101, v149
	v_cvt_rpi_i32_f32_e32 v148, v148
	v_cvt_rpi_i32_f32_e32 v149, v149
	v_mul_f32_e32 v153, s101, v153
	v_lshl_or_b32 v148, v149, 8, v148
	v_mul_f32_e32 v149, s100, v122
	v_exp_f32_e32 v149, v149
	v_cvt_rpi_i32_f32_e32 v153, v153
	v_mul_f32_e32 v154, s100, v115
	v_exp_f32_e32 v154, v154
	v_add_f32_e32 v149, 1.0, v149
	v_rcp_f32_e32 v149, v149
	v_min_u32_sdwa v153, v153, s81 dst_sel:BYTE_3 dst_unused:UNUSED_PAD src0_sel:DWORD src1_sel:DWORD
	v_add_f32_e32 v154, 1.0, v154
	v_rcp_f32_e32 v154, v154
	v_mul_f32_e32 v149, s101, v149
	v_cvt_rpi_i32_f32_e32 v149, v149
	v_mul_f32_e32 v154, s101, v154
	v_cvt_rpi_i32_f32_e32 v154, v154
	v_min_u32_sdwa v149, v149, s81 dst_sel:WORD_1 dst_unused:UNUSED_PAD src0_sel:DWORD src1_sel:DWORD
	v_or3_b32 v145, v146, v145, v144
	v_or3_b32 v149, v148, v149, v152
	v_bitop3_b32 v148, v150, v144, 1 bitop3:0x36
	v_lshl_add_u32 v148, v148, 4, v151
	ds_write_b32 v148, v149
	v_mul_f32_e32 v149, s100, v116
	v_mul_f32_e32 v152, s100, v117
	v_exp_f32_e32 v149, v149
	v_exp_f32_e32 v152, v152
	v_min_u32_sdwa v154, v154, s81 dst_sel:BYTE_3 dst_unused:UNUSED_PAD src0_sel:DWORD src1_sel:DWORD
	v_lshlrev_b32_e32 v146, 4, v144
	v_add_f32_e32 v149, 1.0, v149
	v_add_f32_e32 v152, 1.0, v152
	v_rcp_f32_e32 v149, v149
	v_rcp_f32_e32 v152, v152
	s_and_b32 s17, s13, 0xffff
	s_mov_b32 s16, s12
	v_mul_f32_e32 v149, s101, v149
	v_mul_f32_e32 v152, s101, v152
	v_cvt_rpi_i32_f32_e32 v149, v149
	v_cvt_rpi_i32_f32_e32 v152, v152
	s_mov_b32 s18, s10
	s_mov_b32 s19, s11
	v_lshl_or_b32 v149, v152, 8, v149
	v_mul_f32_e32 v152, s100, v118
	v_exp_f32_e32 v152, v152
	s_nop 0
	v_add_f32_e32 v152, 1.0, v152
	v_rcp_f32_e32 v152, v152
	s_nop 0
	v_mul_f32_e32 v152, s101, v152
	v_cvt_rpi_i32_f32_e32 v152, v152
	v_min_u32_sdwa v152, v152, s81 dst_sel:WORD_1 dst_unused:UNUSED_PAD src0_sel:DWORD src1_sel:DWORD
	s_nop 0
	v_or3_b32 v152, v149, v152, v153
	v_bitop3_b32 v149, v150, v144, 2 bitop3:0x36
	v_lshl_add_u32 v149, v149, 4, v151
	ds_write_b32 v149, v152
	v_mul_f32_e32 v152, s100, v112
	v_mul_f32_e32 v153, s100, v113
	v_exp_f32_e32 v152, v152
	v_exp_f32_e32 v153, v153
	v_bitop3_b32 v150, v150, v144, 3 bitop3:0x36
	v_lshl_add_u32 v150, v150, 4, v151
	v_add_f32_e32 v152, 1.0, v152
	v_add_f32_e32 v153, 1.0, v153
	v_rcp_f32_e32 v152, v152
	v_rcp_f32_e32 v153, v153
	v_mul_f32_e32 v151, s100, v108
	v_exp_f32_e32 v151, v151
	v_mul_f32_e32 v152, s101, v152
	v_mul_f32_e32 v153, s101, v153
	v_cvt_rpi_i32_f32_e32 v152, v152
	v_cvt_rpi_i32_f32_e32 v153, v153
	v_add_f32_e32 v151, 1.0, v151
	v_rcp_f32_e32 v151, v151
	v_lshl_or_b32 v152, v153, 8, v152
	v_mul_f32_e32 v153, s100, v114
	v_exp_f32_e32 v153, v153
	v_mul_f32_e32 v151, s101, v151
	v_cvt_rpi_i32_f32_e32 v151, v151
	v_add_f32_e32 v153, 1.0, v153
	v_rcp_f32_e32 v153, v153
	s_nop 0
	v_mul_f32_e32 v153, s101, v153
	v_cvt_rpi_i32_f32_e32 v153, v153
	v_min_u32_sdwa v153, v153, s81 dst_sel:WORD_1 dst_unused:UNUSED_PAD src0_sel:DWORD src1_sel:DWORD
	s_nop 0
	v_or3_b32 v152, v152, v153, v154
	ds_write_b32 v150, v152
	v_mul_f32_e32 v152, s100, v109
	v_exp_f32_e32 v152, v152
	v_mul_f32_e32 v153, s100, v111
	v_exp_f32_e32 v153, v153
	v_add_f32_e32 v152, 1.0, v152
	v_rcp_f32_e32 v152, v152
	v_add_f32_e32 v153, 1.0, v153
	v_rcp_f32_e32 v153, v153
	v_mul_f32_e32 v152, s101, v152
	v_cvt_rpi_i32_f32_e32 v152, v152
	v_mul_f32_e32 v153, s101, v153
	v_cvt_rpi_i32_f32_e32 v153, v153
	v_lshl_or_b32 v151, v152, 8, v151
	v_mul_f32_e32 v152, s100, v110
	v_exp_f32_e32 v152, v152
	v_min_u32_sdwa v153, v153, s81 dst_sel:BYTE_3 dst_unused:UNUSED_PAD src0_sel:DWORD src1_sel:DWORD
	v_add_f32_e32 v152, 1.0, v152
	v_rcp_f32_e32 v152, v152
	s_nop 0
	v_mul_f32_e32 v152, s101, v152
	v_cvt_rpi_i32_f32_e32 v152, v152
	v_min_u32_sdwa v152, v152, s81 dst_sel:WORD_1 dst_unused:UNUSED_PAD src0_sel:DWORD src1_sel:DWORD
	s_nop 0
	v_or3_b32 v151, v151, v152, v153
	ds_write_b32 v147, v151 offset:4096
	v_mul_f32_e32 v151, s100, v104
	v_mul_f32_e32 v152, s100, v105
	v_exp_f32_e32 v151, v151
	v_exp_f32_e32 v152, v152
	v_mul_f32_e32 v153, s100, v107
	v_exp_f32_e32 v153, v153
	v_add_f32_e32 v151, 1.0, v151
	v_add_f32_e32 v152, 1.0, v152
	v_rcp_f32_e32 v151, v151
	v_rcp_f32_e32 v152, v152
	v_add_f32_e32 v153, 1.0, v153
	v_rcp_f32_e32 v153, v153
	v_mul_f32_e32 v151, s101, v151
	v_mul_f32_e32 v152, s101, v152
	v_cvt_rpi_i32_f32_e32 v151, v151
	v_cvt_rpi_i32_f32_e32 v152, v152
	v_mul_f32_e32 v153, s101, v153
	v_lshl_or_b32 v151, v152, 8, v151
	v_mul_f32_e32 v152, s100, v106
	v_exp_f32_e32 v152, v152
	v_cvt_rpi_i32_f32_e32 v153, v153
	v_add_f32_e32 v152, 1.0, v152
	v_rcp_f32_e32 v152, v152
	v_min_u32_sdwa v153, v153, s81 dst_sel:BYTE_3 dst_unused:UNUSED_PAD src0_sel:DWORD src1_sel:DWORD
	v_mul_f32_e32 v152, s101, v152
	v_cvt_rpi_i32_f32_e32 v152, v152
	v_min_u32_sdwa v152, v152, s81 dst_sel:WORD_1 dst_unused:UNUSED_PAD src0_sel:DWORD src1_sel:DWORD
	s_nop 0
	v_or3_b32 v151, v151, v152, v153
	ds_write_b32 v148, v151 offset:4096
	v_mul_f32_e32 v151, s100, v100
	v_mul_f32_e32 v152, s100, v101
	v_exp_f32_e32 v151, v151
	v_exp_f32_e32 v152, v152
	v_mul_f32_e32 v153, s100, v103
	v_exp_f32_e32 v153, v153
	v_add_f32_e32 v151, 1.0, v151
	v_add_f32_e32 v152, 1.0, v152
	v_rcp_f32_e32 v151, v151
	v_rcp_f32_e32 v152, v152
	v_add_f32_e32 v153, 1.0, v153
	v_rcp_f32_e32 v153, v153
	v_mul_f32_e32 v151, s101, v151
	v_mul_f32_e32 v152, s101, v152
	v_cvt_rpi_i32_f32_e32 v151, v151
	v_cvt_rpi_i32_f32_e32 v152, v152
	v_mul_f32_e32 v153, s101, v153
	v_lshl_or_b32 v151, v152, 8, v151
	v_mul_f32_e32 v152, s100, v102
	v_exp_f32_e32 v152, v152
	v_cvt_rpi_i32_f32_e32 v153, v153
	v_add_f32_e32 v152, 1.0, v152
	v_rcp_f32_e32 v152, v152
	v_min_u32_sdwa v153, v153, s81 dst_sel:BYTE_3 dst_unused:UNUSED_PAD src0_sel:DWORD src1_sel:DWORD
	v_mul_f32_e32 v152, s101, v152
	v_cvt_rpi_i32_f32_e32 v152, v152
	v_min_u32_sdwa v152, v152, s81 dst_sel:WORD_1 dst_unused:UNUSED_PAD src0_sel:DWORD src1_sel:DWORD
	s_nop 0
	v_or3_b32 v151, v151, v152, v153
	ds_write_b32 v149, v151 offset:4096
	v_mul_f32_e32 v151, s100, v96
	v_mul_f32_e32 v152, s100, v97
	v_exp_f32_e32 v151, v151
	v_exp_f32_e32 v152, v152
	v_mul_f32_e32 v153, s100, v99
	v_exp_f32_e32 v153, v153
	v_add_f32_e32 v151, 1.0, v151
	v_add_f32_e32 v152, 1.0, v152
	v_rcp_f32_e32 v151, v151
	v_rcp_f32_e32 v152, v152
	v_add_f32_e32 v153, 1.0, v153
	v_rcp_f32_e32 v153, v153
	v_mul_f32_e32 v151, s101, v151
	v_mul_f32_e32 v152, s101, v152
	v_cvt_rpi_i32_f32_e32 v151, v151
	v_cvt_rpi_i32_f32_e32 v152, v152
	v_mul_f32_e32 v153, s101, v153
	v_lshl_or_b32 v151, v152, 8, v151
	v_mul_f32_e32 v152, s100, v98
	v_exp_f32_e32 v152, v152
	v_cvt_rpi_i32_f32_e32 v153, v153
	v_add_f32_e32 v152, 1.0, v152
	v_rcp_f32_e32 v152, v152
	v_min_u32_sdwa v153, v153, s81 dst_sel:BYTE_3 dst_unused:UNUSED_PAD src0_sel:DWORD src1_sel:DWORD
	v_mul_f32_e32 v152, s101, v152
	v_cvt_rpi_i32_f32_e32 v152, v152
	v_min_u32_sdwa v152, v152, s81 dst_sel:WORD_1 dst_unused:UNUSED_PAD src0_sel:DWORD src1_sel:DWORD
	s_nop 0
	v_or3_b32 v151, v151, v152, v153
	ds_write_b32 v150, v151 offset:4096
	v_mul_f32_e32 v151, s100, v92
	v_mul_f32_e32 v152, s100, v93
	v_exp_f32_e32 v151, v151
	v_exp_f32_e32 v152, v152
	v_mul_f32_e32 v153, s100, v95
	v_exp_f32_e32 v153, v153
	v_add_f32_e32 v151, 1.0, v151
	v_add_f32_e32 v152, 1.0, v152
	v_rcp_f32_e32 v151, v151
	v_rcp_f32_e32 v152, v152
	v_add_f32_e32 v153, 1.0, v153
	v_rcp_f32_e32 v153, v153
	v_mul_f32_e32 v151, s101, v151
	v_mul_f32_e32 v152, s101, v152
	v_cvt_rpi_i32_f32_e32 v151, v151
	v_cvt_rpi_i32_f32_e32 v152, v152
	v_mul_f32_e32 v153, s101, v153
	v_lshl_or_b32 v151, v152, 8, v151
	v_mul_f32_e32 v152, s100, v94
	v_exp_f32_e32 v152, v152
	v_cvt_rpi_i32_f32_e32 v153, v153
	v_add_f32_e32 v152, 1.0, v152
	v_rcp_f32_e32 v152, v152
	v_min_u32_sdwa v153, v153, s81 dst_sel:BYTE_3 dst_unused:UNUSED_PAD src0_sel:DWORD src1_sel:DWORD
	v_mul_f32_e32 v152, s101, v152
	v_cvt_rpi_i32_f32_e32 v152, v152
	v_min_u32_sdwa v152, v152, s81 dst_sel:WORD_1 dst_unused:UNUSED_PAD src0_sel:DWORD src1_sel:DWORD
	s_nop 0
	v_or3_b32 v151, v151, v152, v153
	ds_write_b32 v147, v151 offset:8192
	v_mul_f32_e32 v151, s100, v88
	v_mul_f32_e32 v152, s100, v89
	v_exp_f32_e32 v151, v151
	v_exp_f32_e32 v152, v152
	v_mul_f32_e32 v153, s100, v91
	v_exp_f32_e32 v153, v153
	v_add_f32_e32 v151, 1.0, v151
	v_add_f32_e32 v152, 1.0, v152
	v_rcp_f32_e32 v151, v151
	v_rcp_f32_e32 v152, v152
	v_add_f32_e32 v153, 1.0, v153
	v_rcp_f32_e32 v153, v153
	v_mul_f32_e32 v151, s101, v151
	v_mul_f32_e32 v152, s101, v152
	v_cvt_rpi_i32_f32_e32 v151, v151
	v_cvt_rpi_i32_f32_e32 v152, v152
	v_mul_f32_e32 v153, s101, v153
	v_lshl_or_b32 v151, v152, 8, v151
	v_mul_f32_e32 v152, s100, v90
	v_exp_f32_e32 v152, v152
	v_cvt_rpi_i32_f32_e32 v153, v153
	v_add_f32_e32 v152, 1.0, v152
	v_rcp_f32_e32 v152, v152
	v_min_u32_sdwa v153, v153, s81 dst_sel:BYTE_3 dst_unused:UNUSED_PAD src0_sel:DWORD src1_sel:DWORD
	v_mul_f32_e32 v152, s101, v152
	v_cvt_rpi_i32_f32_e32 v152, v152
	v_min_u32_sdwa v152, v152, s81 dst_sel:WORD_1 dst_unused:UNUSED_PAD src0_sel:DWORD src1_sel:DWORD
	s_nop 0
	v_or3_b32 v151, v151, v152, v153
	ds_write_b32 v148, v151 offset:8192
	v_mul_f32_e32 v151, s100, v84
	v_mul_f32_e32 v152, s100, v85
	v_exp_f32_e32 v151, v151
	v_exp_f32_e32 v152, v152
	v_mul_f32_e32 v153, s100, v87
	v_exp_f32_e32 v153, v153
	v_add_f32_e32 v151, 1.0, v151
	v_add_f32_e32 v152, 1.0, v152
	v_rcp_f32_e32 v151, v151
	v_rcp_f32_e32 v152, v152
	v_add_f32_e32 v153, 1.0, v153
	v_rcp_f32_e32 v153, v153
	v_mul_f32_e32 v151, s101, v151
	v_mul_f32_e32 v152, s101, v152
	v_cvt_rpi_i32_f32_e32 v151, v151
	v_cvt_rpi_i32_f32_e32 v152, v152
	v_mul_f32_e32 v153, s101, v153
	v_lshl_or_b32 v151, v152, 8, v151
	v_mul_f32_e32 v152, s100, v86
	v_exp_f32_e32 v152, v152
	v_cvt_rpi_i32_f32_e32 v153, v153
	v_add_f32_e32 v152, 1.0, v152
	v_rcp_f32_e32 v152, v152
	v_min_u32_sdwa v153, v153, s81 dst_sel:BYTE_3 dst_unused:UNUSED_PAD src0_sel:DWORD src1_sel:DWORD
	v_mul_f32_e32 v152, s101, v152
	v_cvt_rpi_i32_f32_e32 v152, v152
	v_min_u32_sdwa v152, v152, s81 dst_sel:WORD_1 dst_unused:UNUSED_PAD src0_sel:DWORD src1_sel:DWORD
	s_nop 0
	v_or3_b32 v151, v151, v152, v153
	ds_write_b32 v149, v151 offset:8192
	v_mul_f32_e32 v151, s100, v80
	v_mul_f32_e32 v152, s100, v81
	v_exp_f32_e32 v151, v151
	v_exp_f32_e32 v152, v152
	v_mul_f32_e32 v153, s100, v83
	v_exp_f32_e32 v153, v153
	v_add_f32_e32 v151, 1.0, v151
	v_add_f32_e32 v152, 1.0, v152
	v_rcp_f32_e32 v151, v151
	v_rcp_f32_e32 v152, v152
	v_add_f32_e32 v153, 1.0, v153
	v_rcp_f32_e32 v153, v153
	v_mul_f32_e32 v151, s101, v151
	v_mul_f32_e32 v152, s101, v152
	v_cvt_rpi_i32_f32_e32 v151, v151
	v_cvt_rpi_i32_f32_e32 v152, v152
	v_mul_f32_e32 v153, s101, v153
	v_lshl_or_b32 v151, v152, 8, v151
	v_mul_f32_e32 v152, s100, v82
	v_exp_f32_e32 v152, v152
	v_cvt_rpi_i32_f32_e32 v153, v153
	v_add_f32_e32 v152, 1.0, v152
	v_rcp_f32_e32 v152, v152
	v_min_u32_sdwa v153, v153, s81 dst_sel:BYTE_3 dst_unused:UNUSED_PAD src0_sel:DWORD src1_sel:DWORD
	v_mul_f32_e32 v152, s101, v152
	v_cvt_rpi_i32_f32_e32 v152, v152
	v_min_u32_sdwa v152, v152, s81 dst_sel:WORD_1 dst_unused:UNUSED_PAD src0_sel:DWORD src1_sel:DWORD
	s_nop 0
	v_or3_b32 v151, v151, v152, v153
	ds_write_b32 v150, v151 offset:8192
	v_mul_f32_e32 v151, s100, v76
	v_mul_f32_e32 v152, s100, v77
	v_exp_f32_e32 v151, v151
	v_exp_f32_e32 v152, v152
	v_mul_f32_e32 v153, s100, v79
	v_exp_f32_e32 v153, v153
	v_add_f32_e32 v151, 1.0, v151
	v_add_f32_e32 v152, 1.0, v152
	v_rcp_f32_e32 v151, v151
	v_rcp_f32_e32 v152, v152
	v_add_f32_e32 v153, 1.0, v153
	v_rcp_f32_e32 v153, v153
	v_mul_f32_e32 v151, s101, v151
	v_mul_f32_e32 v152, s101, v152
	v_cvt_rpi_i32_f32_e32 v151, v151
	v_cvt_rpi_i32_f32_e32 v152, v152
	v_mul_f32_e32 v153, s101, v153
	v_lshl_or_b32 v151, v152, 8, v151
	v_mul_f32_e32 v152, s100, v78
	v_exp_f32_e32 v152, v152
	v_cvt_rpi_i32_f32_e32 v153, v153
	v_add_f32_e32 v152, 1.0, v152
	v_rcp_f32_e32 v152, v152
	v_min_u32_sdwa v153, v153, s81 dst_sel:BYTE_3 dst_unused:UNUSED_PAD src0_sel:DWORD src1_sel:DWORD
	v_mul_f32_e32 v152, s101, v152
	v_cvt_rpi_i32_f32_e32 v152, v152
	v_min_u32_sdwa v152, v152, s81 dst_sel:WORD_1 dst_unused:UNUSED_PAD src0_sel:DWORD src1_sel:DWORD
	s_nop 0
	v_or3_b32 v151, v151, v152, v153
	ds_write_b32 v147, v151 offset:12288
	v_mul_f32_e32 v151, s100, v72
	v_mul_f32_e32 v152, s100, v73
	v_exp_f32_e32 v151, v151
	v_exp_f32_e32 v152, v152
	v_mul_f32_e32 v153, s100, v75
	v_exp_f32_e32 v153, v153
	v_add_f32_e32 v151, 1.0, v151
	v_add_f32_e32 v152, 1.0, v152
	v_rcp_f32_e32 v151, v151
	v_rcp_f32_e32 v152, v152
	v_add_f32_e32 v153, 1.0, v153
	v_rcp_f32_e32 v153, v153
	v_mul_f32_e32 v151, s101, v151
	v_mul_f32_e32 v152, s101, v152
	v_cvt_rpi_i32_f32_e32 v151, v151
	v_cvt_rpi_i32_f32_e32 v152, v152
	v_mul_f32_e32 v153, s101, v153
	v_lshl_or_b32 v151, v152, 8, v151
	v_mul_f32_e32 v152, s100, v74
	v_exp_f32_e32 v152, v152
	v_cvt_rpi_i32_f32_e32 v153, v153
	v_add_f32_e32 v152, 1.0, v152
	v_rcp_f32_e32 v152, v152
	v_min_u32_sdwa v153, v153, s81 dst_sel:BYTE_3 dst_unused:UNUSED_PAD src0_sel:DWORD src1_sel:DWORD
	v_mul_f32_e32 v152, s101, v152
	v_cvt_rpi_i32_f32_e32 v152, v152
	v_min_u32_sdwa v152, v152, s81 dst_sel:WORD_1 dst_unused:UNUSED_PAD src0_sel:DWORD src1_sel:DWORD
	s_nop 0
	v_or3_b32 v151, v151, v152, v153
	ds_write_b32 v148, v151 offset:12288
	v_mul_f32_e32 v151, s100, v68
	v_mul_f32_e32 v152, s100, v69
	v_exp_f32_e32 v151, v151
	v_exp_f32_e32 v152, v152
	v_mul_f32_e32 v153, s100, v71
	v_exp_f32_e32 v153, v153
	v_add_f32_e32 v151, 1.0, v151
	v_add_f32_e32 v152, 1.0, v152
	v_rcp_f32_e32 v151, v151
	v_rcp_f32_e32 v152, v152
	v_add_f32_e32 v153, 1.0, v153
	v_rcp_f32_e32 v153, v153
	v_mul_f32_e32 v151, s101, v151
	v_mul_f32_e32 v152, s101, v152
	v_cvt_rpi_i32_f32_e32 v151, v151
	v_cvt_rpi_i32_f32_e32 v152, v152
	v_mul_f32_e32 v153, s101, v153
	v_lshl_or_b32 v151, v152, 8, v151
	v_mul_f32_e32 v152, s100, v70
	v_exp_f32_e32 v152, v152
	v_cvt_rpi_i32_f32_e32 v153, v153
	v_add_f32_e32 v152, 1.0, v152
	v_rcp_f32_e32 v152, v152
	v_min_u32_sdwa v153, v153, s81 dst_sel:BYTE_3 dst_unused:UNUSED_PAD src0_sel:DWORD src1_sel:DWORD
	v_mul_f32_e32 v152, s101, v152
	v_cvt_rpi_i32_f32_e32 v152, v152
	v_min_u32_sdwa v152, v152, s81 dst_sel:WORD_1 dst_unused:UNUSED_PAD src0_sel:DWORD src1_sel:DWORD
	s_nop 0
	v_or3_b32 v151, v151, v152, v153
	ds_write_b32 v149, v151 offset:12288
	v_mul_f32_e32 v151, s100, v64
	v_mul_f32_e32 v152, s100, v65
	v_exp_f32_e32 v151, v151
	v_exp_f32_e32 v152, v152
	v_mul_f32_e32 v153, s100, v67
	v_exp_f32_e32 v153, v153
	v_add_f32_e32 v151, 1.0, v151
	v_add_f32_e32 v152, 1.0, v152
	v_rcp_f32_e32 v151, v151
	v_rcp_f32_e32 v152, v152
	v_add_f32_e32 v153, 1.0, v153
	v_rcp_f32_e32 v153, v153
	v_mul_f32_e32 v151, s101, v151
	v_mul_f32_e32 v152, s101, v152
	v_cvt_rpi_i32_f32_e32 v151, v151
	v_cvt_rpi_i32_f32_e32 v152, v152
	v_mul_f32_e32 v153, s101, v153
	v_lshl_or_b32 v151, v152, 8, v151
	v_mul_f32_e32 v152, s100, v66
	v_exp_f32_e32 v152, v152
	v_cvt_rpi_i32_f32_e32 v153, v153
	v_add_f32_e32 v152, 1.0, v152
	v_rcp_f32_e32 v152, v152
	v_min_u32_sdwa v153, v153, s81 dst_sel:BYTE_3 dst_unused:UNUSED_PAD src0_sel:DWORD src1_sel:DWORD
	v_mul_f32_e32 v152, s101, v152
	v_cvt_rpi_i32_f32_e32 v152, v152
	v_min_u32_sdwa v152, v152, s81 dst_sel:WORD_1 dst_unused:UNUSED_PAD src0_sel:DWORD src1_sel:DWORD
	s_nop 0
	v_or3_b32 v151, v151, v152, v153
	ds_write_b32 v150, v151 offset:12288
	v_mul_f32_e32 v151, s100, v60
	v_mul_f32_e32 v152, s100, v61
	v_exp_f32_e32 v151, v151
	v_exp_f32_e32 v152, v152
	v_mul_f32_e32 v153, s100, v63
	v_exp_f32_e32 v153, v153
	v_add_f32_e32 v151, 1.0, v151
	v_add_f32_e32 v152, 1.0, v152
	v_rcp_f32_e32 v151, v151
	v_rcp_f32_e32 v152, v152
	v_add_f32_e32 v153, 1.0, v153
	v_rcp_f32_e32 v153, v153
	v_mul_f32_e32 v151, s101, v151
	v_mul_f32_e32 v152, s101, v152
	v_cvt_rpi_i32_f32_e32 v151, v151
	v_cvt_rpi_i32_f32_e32 v152, v152
	v_mul_f32_e32 v153, s101, v153
	v_lshl_or_b32 v151, v152, 8, v151
	v_mul_f32_e32 v152, s100, v62
	v_exp_f32_e32 v152, v152
	v_cvt_rpi_i32_f32_e32 v153, v153
	v_add_f32_e32 v152, 1.0, v152
	v_rcp_f32_e32 v152, v152
	v_min_u32_sdwa v153, v153, s81 dst_sel:BYTE_3 dst_unused:UNUSED_PAD src0_sel:DWORD src1_sel:DWORD
	v_mul_f32_e32 v152, s101, v152
	v_cvt_rpi_i32_f32_e32 v152, v152
	v_min_u32_sdwa v152, v152, s81 dst_sel:WORD_1 dst_unused:UNUSED_PAD src0_sel:DWORD src1_sel:DWORD
	s_nop 0
	v_or3_b32 v151, v151, v152, v153
	ds_write_b32 v147, v151 offset:16384
	v_mul_f32_e32 v151, s100, v56
	v_mul_f32_e32 v152, s100, v57
	v_exp_f32_e32 v151, v151
	v_exp_f32_e32 v152, v152
	v_mul_f32_e32 v153, s100, v59
	v_exp_f32_e32 v153, v153
	v_add_f32_e32 v151, 1.0, v151
	v_add_f32_e32 v152, 1.0, v152
	v_rcp_f32_e32 v151, v151
	v_rcp_f32_e32 v152, v152
	v_add_f32_e32 v153, 1.0, v153
	v_rcp_f32_e32 v153, v153
	v_mul_f32_e32 v151, s101, v151
	v_mul_f32_e32 v152, s101, v152
	v_cvt_rpi_i32_f32_e32 v151, v151
	v_cvt_rpi_i32_f32_e32 v152, v152
	v_mul_f32_e32 v153, s101, v153
	v_lshl_or_b32 v151, v152, 8, v151
	v_mul_f32_e32 v152, s100, v58
	v_exp_f32_e32 v152, v152
	v_cvt_rpi_i32_f32_e32 v153, v153
	v_add_f32_e32 v152, 1.0, v152
	v_rcp_f32_e32 v152, v152
	v_min_u32_sdwa v153, v153, s81 dst_sel:BYTE_3 dst_unused:UNUSED_PAD src0_sel:DWORD src1_sel:DWORD
	v_mul_f32_e32 v152, s101, v152
	v_cvt_rpi_i32_f32_e32 v152, v152
	v_min_u32_sdwa v152, v152, s81 dst_sel:WORD_1 dst_unused:UNUSED_PAD src0_sel:DWORD src1_sel:DWORD
	s_nop 0
	v_or3_b32 v151, v151, v152, v153
	ds_write_b32 v148, v151 offset:16384
	v_mul_f32_e32 v151, s100, v52
	v_mul_f32_e32 v152, s100, v53
	v_exp_f32_e32 v151, v151
	v_exp_f32_e32 v152, v152
	v_mul_f32_e32 v153, s100, v55
	v_exp_f32_e32 v153, v153
	v_add_f32_e32 v151, 1.0, v151
	v_add_f32_e32 v152, 1.0, v152
	v_rcp_f32_e32 v151, v151
	v_rcp_f32_e32 v152, v152
	v_add_f32_e32 v153, 1.0, v153
	v_rcp_f32_e32 v153, v153
	v_mul_f32_e32 v151, s101, v151
	v_mul_f32_e32 v152, s101, v152
	v_cvt_rpi_i32_f32_e32 v151, v151
	v_cvt_rpi_i32_f32_e32 v152, v152
	v_mul_f32_e32 v153, s101, v153
	v_lshl_or_b32 v151, v152, 8, v151
	v_mul_f32_e32 v152, s100, v54
	v_exp_f32_e32 v152, v152
	v_cvt_rpi_i32_f32_e32 v153, v153
	v_add_f32_e32 v152, 1.0, v152
	v_rcp_f32_e32 v152, v152
	v_min_u32_sdwa v153, v153, s81 dst_sel:BYTE_3 dst_unused:UNUSED_PAD src0_sel:DWORD src1_sel:DWORD
	v_mul_f32_e32 v152, s101, v152
	v_cvt_rpi_i32_f32_e32 v152, v152
	v_min_u32_sdwa v152, v152, s81 dst_sel:WORD_1 dst_unused:UNUSED_PAD src0_sel:DWORD src1_sel:DWORD
	s_nop 0
	v_or3_b32 v151, v151, v152, v153
	ds_write_b32 v149, v151 offset:16384
	v_mul_f32_e32 v151, s100, v48
	v_mul_f32_e32 v152, s100, v49
	v_exp_f32_e32 v151, v151
	v_exp_f32_e32 v152, v152
	v_mul_f32_e32 v153, s100, v51
	v_exp_f32_e32 v153, v153
	v_add_f32_e32 v151, 1.0, v151
	v_add_f32_e32 v152, 1.0, v152
	v_rcp_f32_e32 v151, v151
	v_rcp_f32_e32 v152, v152
	v_add_f32_e32 v153, 1.0, v153
	v_rcp_f32_e32 v153, v153
	v_mul_f32_e32 v151, s101, v151
	v_mul_f32_e32 v152, s101, v152
	v_cvt_rpi_i32_f32_e32 v151, v151
	v_cvt_rpi_i32_f32_e32 v152, v152
	v_mul_f32_e32 v153, s101, v153
	v_lshl_or_b32 v151, v152, 8, v151
	v_mul_f32_e32 v152, s100, v50
	v_exp_f32_e32 v152, v152
	v_cvt_rpi_i32_f32_e32 v153, v153
	v_add_f32_e32 v152, 1.0, v152
	v_rcp_f32_e32 v152, v152
	v_min_u32_sdwa v153, v153, s81 dst_sel:BYTE_3 dst_unused:UNUSED_PAD src0_sel:DWORD src1_sel:DWORD
	v_mul_f32_e32 v152, s101, v152
	v_cvt_rpi_i32_f32_e32 v152, v152
	v_min_u32_sdwa v152, v152, s81 dst_sel:WORD_1 dst_unused:UNUSED_PAD src0_sel:DWORD src1_sel:DWORD
	s_nop 0
	v_or3_b32 v151, v151, v152, v153
	ds_write_b32 v150, v151 offset:16384
	v_mul_f32_e32 v151, s100, v44
	v_mul_f32_e32 v152, s100, v45
	v_exp_f32_e32 v151, v151
	v_exp_f32_e32 v152, v152
	v_mul_f32_e32 v153, s100, v47
	v_exp_f32_e32 v153, v153
	v_add_f32_e32 v151, 1.0, v151
	v_add_f32_e32 v152, 1.0, v152
	v_rcp_f32_e32 v151, v151
	v_rcp_f32_e32 v152, v152
	v_add_f32_e32 v153, 1.0, v153
	v_rcp_f32_e32 v153, v153
	v_mul_f32_e32 v151, s101, v151
	v_mul_f32_e32 v152, s101, v152
	v_cvt_rpi_i32_f32_e32 v151, v151
	v_cvt_rpi_i32_f32_e32 v152, v152
	v_mul_f32_e32 v153, s101, v153
	v_lshl_or_b32 v151, v152, 8, v151
	v_mul_f32_e32 v152, s100, v46
	v_exp_f32_e32 v152, v152
	v_cvt_rpi_i32_f32_e32 v153, v153
	v_add_f32_e32 v152, 1.0, v152
	v_rcp_f32_e32 v152, v152
	v_min_u32_sdwa v153, v153, s81 dst_sel:BYTE_3 dst_unused:UNUSED_PAD src0_sel:DWORD src1_sel:DWORD
	v_mul_f32_e32 v152, s101, v152
	v_cvt_rpi_i32_f32_e32 v152, v152
	v_min_u32_sdwa v152, v152, s81 dst_sel:WORD_1 dst_unused:UNUSED_PAD src0_sel:DWORD src1_sel:DWORD
	s_nop 0
	v_or3_b32 v151, v151, v152, v153
	ds_write_b32 v147, v151 offset:20480
	v_mul_f32_e32 v151, s100, v40
	v_mul_f32_e32 v152, s100, v41
	v_exp_f32_e32 v151, v151
	v_exp_f32_e32 v152, v152
	v_mul_f32_e32 v153, s100, v43
	v_exp_f32_e32 v153, v153
	v_add_f32_e32 v151, 1.0, v151
	v_add_f32_e32 v152, 1.0, v152
	v_rcp_f32_e32 v151, v151
	v_rcp_f32_e32 v152, v152
	v_add_f32_e32 v153, 1.0, v153
	v_rcp_f32_e32 v153, v153
	v_mul_f32_e32 v151, s101, v151
	v_mul_f32_e32 v152, s101, v152
	v_cvt_rpi_i32_f32_e32 v151, v151
	v_cvt_rpi_i32_f32_e32 v152, v152
	v_mul_f32_e32 v153, s101, v153
	v_lshl_or_b32 v151, v152, 8, v151
	v_mul_f32_e32 v152, s100, v42
	v_exp_f32_e32 v152, v152
	v_cvt_rpi_i32_f32_e32 v153, v153
	v_add_f32_e32 v152, 1.0, v152
	v_rcp_f32_e32 v152, v152
	v_min_u32_sdwa v153, v153, s81 dst_sel:BYTE_3 dst_unused:UNUSED_PAD src0_sel:DWORD src1_sel:DWORD
	v_mul_f32_e32 v152, s101, v152
	v_cvt_rpi_i32_f32_e32 v152, v152
	v_min_u32_sdwa v152, v152, s81 dst_sel:WORD_1 dst_unused:UNUSED_PAD src0_sel:DWORD src1_sel:DWORD
	s_nop 0
	v_or3_b32 v151, v151, v152, v153
	ds_write_b32 v148, v151 offset:20480
	v_mul_f32_e32 v151, s100, v36
	v_mul_f32_e32 v152, s100, v37
	v_exp_f32_e32 v151, v151
	v_exp_f32_e32 v152, v152
	v_mul_f32_e32 v153, s100, v39
	v_exp_f32_e32 v153, v153
	v_add_f32_e32 v151, 1.0, v151
	v_add_f32_e32 v152, 1.0, v152
	v_rcp_f32_e32 v151, v151
	v_rcp_f32_e32 v152, v152
	v_add_f32_e32 v153, 1.0, v153
	v_rcp_f32_e32 v153, v153
	v_mul_f32_e32 v151, s101, v151
	v_mul_f32_e32 v152, s101, v152
	v_cvt_rpi_i32_f32_e32 v151, v151
	v_cvt_rpi_i32_f32_e32 v152, v152
	v_mul_f32_e32 v153, s101, v153
	v_lshl_or_b32 v151, v152, 8, v151
	v_mul_f32_e32 v152, s100, v38
	v_exp_f32_e32 v152, v152
	v_cvt_rpi_i32_f32_e32 v153, v153
	v_add_f32_e32 v152, 1.0, v152
	v_rcp_f32_e32 v152, v152
	v_min_u32_sdwa v153, v153, s81 dst_sel:BYTE_3 dst_unused:UNUSED_PAD src0_sel:DWORD src1_sel:DWORD
	v_mul_f32_e32 v152, s101, v152
	v_cvt_rpi_i32_f32_e32 v152, v152
	v_min_u32_sdwa v152, v152, s81 dst_sel:WORD_1 dst_unused:UNUSED_PAD src0_sel:DWORD src1_sel:DWORD
	s_nop 0
	v_or3_b32 v151, v151, v152, v153
	ds_write_b32 v149, v151 offset:20480
	v_mul_f32_e32 v151, s100, v32
	v_mul_f32_e32 v152, s100, v33
	v_exp_f32_e32 v151, v151
	v_exp_f32_e32 v152, v152
	v_mul_f32_e32 v153, s100, v35
	v_exp_f32_e32 v153, v153
	v_add_f32_e32 v151, 1.0, v151
	v_add_f32_e32 v152, 1.0, v152
	v_rcp_f32_e32 v151, v151
	v_rcp_f32_e32 v152, v152
	v_add_f32_e32 v153, 1.0, v153
	v_rcp_f32_e32 v153, v153
	v_mul_f32_e32 v151, s101, v151
	v_mul_f32_e32 v152, s101, v152
	v_cvt_rpi_i32_f32_e32 v151, v151
	v_cvt_rpi_i32_f32_e32 v152, v152
	v_mul_f32_e32 v153, s101, v153
	v_lshl_or_b32 v151, v152, 8, v151
	v_mul_f32_e32 v152, s100, v34
	v_exp_f32_e32 v152, v152
	v_cvt_rpi_i32_f32_e32 v153, v153
	v_add_f32_e32 v152, 1.0, v152
	v_rcp_f32_e32 v152, v152
	v_min_u32_sdwa v153, v153, s81 dst_sel:BYTE_3 dst_unused:UNUSED_PAD src0_sel:DWORD src1_sel:DWORD
	v_mul_f32_e32 v152, s101, v152
	v_cvt_rpi_i32_f32_e32 v152, v152
	v_min_u32_sdwa v152, v152, s81 dst_sel:WORD_1 dst_unused:UNUSED_PAD src0_sel:DWORD src1_sel:DWORD
	s_nop 0
	v_or3_b32 v151, v151, v152, v153
	ds_write_b32 v150, v151 offset:20480
	v_mul_f32_e32 v151, s100, v28
	v_mul_f32_e32 v152, s100, v29
	v_exp_f32_e32 v151, v151
	v_exp_f32_e32 v152, v152
	v_mul_f32_e32 v153, s100, v31
	v_exp_f32_e32 v153, v153
	v_add_f32_e32 v151, 1.0, v151
	v_add_f32_e32 v152, 1.0, v152
	v_rcp_f32_e32 v151, v151
	v_rcp_f32_e32 v152, v152
	v_add_f32_e32 v153, 1.0, v153
	v_rcp_f32_e32 v153, v153
	v_mul_f32_e32 v151, s101, v151
	v_mul_f32_e32 v152, s101, v152
	v_cvt_rpi_i32_f32_e32 v151, v151
	v_cvt_rpi_i32_f32_e32 v152, v152
	v_mul_f32_e32 v153, s101, v153
	v_lshl_or_b32 v151, v152, 8, v151
	v_mul_f32_e32 v152, s100, v30
	v_exp_f32_e32 v152, v152
	v_cvt_rpi_i32_f32_e32 v153, v153
	v_add_f32_e32 v152, 1.0, v152
	v_rcp_f32_e32 v152, v152
	v_min_u32_sdwa v153, v153, s81 dst_sel:BYTE_3 dst_unused:UNUSED_PAD src0_sel:DWORD src1_sel:DWORD
	v_mul_f32_e32 v152, s101, v152
	v_cvt_rpi_i32_f32_e32 v152, v152
	v_min_u32_sdwa v152, v152, s81 dst_sel:WORD_1 dst_unused:UNUSED_PAD src0_sel:DWORD src1_sel:DWORD
	s_nop 0
	v_or3_b32 v151, v151, v152, v153
	ds_write_b32 v147, v151 offset:24576
	v_mul_f32_e32 v151, s100, v24
	v_mul_f32_e32 v152, s100, v25
	v_exp_f32_e32 v151, v151
	v_exp_f32_e32 v152, v152
	v_mul_f32_e32 v153, s100, v27
	v_exp_f32_e32 v153, v153
	v_add_f32_e32 v151, 1.0, v151
	v_add_f32_e32 v152, 1.0, v152
	v_rcp_f32_e32 v151, v151
	v_rcp_f32_e32 v152, v152
	v_add_f32_e32 v153, 1.0, v153
	v_rcp_f32_e32 v153, v153
	v_mul_f32_e32 v151, s101, v151
	v_mul_f32_e32 v152, s101, v152
	v_cvt_rpi_i32_f32_e32 v151, v151
	v_cvt_rpi_i32_f32_e32 v152, v152
	v_mul_f32_e32 v153, s101, v153
	v_lshl_or_b32 v151, v152, 8, v151
	v_mul_f32_e32 v152, s100, v26
	v_exp_f32_e32 v152, v152
	v_cvt_rpi_i32_f32_e32 v153, v153
	v_add_f32_e32 v152, 1.0, v152
	v_rcp_f32_e32 v152, v152
	v_min_u32_sdwa v153, v153, s81 dst_sel:BYTE_3 dst_unused:UNUSED_PAD src0_sel:DWORD src1_sel:DWORD
	v_mul_f32_e32 v152, s101, v152
	v_cvt_rpi_i32_f32_e32 v152, v152
	v_min_u32_sdwa v152, v152, s81 dst_sel:WORD_1 dst_unused:UNUSED_PAD src0_sel:DWORD src1_sel:DWORD
	s_nop 0
	v_or3_b32 v151, v151, v152, v153
	ds_write_b32 v148, v151 offset:24576
	v_mul_f32_e32 v151, s100, v20
	v_mul_f32_e32 v152, s100, v21
	v_exp_f32_e32 v151, v151
	v_exp_f32_e32 v152, v152
	v_mul_f32_e32 v153, s100, v23
	v_exp_f32_e32 v153, v153
	v_add_f32_e32 v151, 1.0, v151
	v_add_f32_e32 v152, 1.0, v152
	v_rcp_f32_e32 v151, v151
	v_rcp_f32_e32 v152, v152
	v_add_f32_e32 v153, 1.0, v153
	v_rcp_f32_e32 v153, v153
	v_mul_f32_e32 v151, s101, v151
	v_mul_f32_e32 v152, s101, v152
	v_cvt_rpi_i32_f32_e32 v151, v151
	v_cvt_rpi_i32_f32_e32 v152, v152
	v_mul_f32_e32 v153, s101, v153
	v_lshl_or_b32 v151, v152, 8, v151
	v_mul_f32_e32 v152, s100, v22
	v_exp_f32_e32 v152, v152
	v_cvt_rpi_i32_f32_e32 v153, v153
	v_add_f32_e32 v152, 1.0, v152
	v_rcp_f32_e32 v152, v152
	v_min_u32_sdwa v153, v153, s81 dst_sel:BYTE_3 dst_unused:UNUSED_PAD src0_sel:DWORD src1_sel:DWORD
	v_mul_f32_e32 v152, s101, v152
	v_cvt_rpi_i32_f32_e32 v152, v152
	v_min_u32_sdwa v152, v152, s81 dst_sel:WORD_1 dst_unused:UNUSED_PAD src0_sel:DWORD src1_sel:DWORD
	s_nop 0
	v_or3_b32 v151, v151, v152, v153
	ds_write_b32 v149, v151 offset:24576
	v_mul_f32_e32 v151, s100, v16
	v_mul_f32_e32 v152, s100, v17
	v_exp_f32_e32 v151, v151
	v_exp_f32_e32 v152, v152
	v_mul_f32_e32 v153, s100, v19
	v_exp_f32_e32 v153, v153
	v_add_f32_e32 v151, 1.0, v151
	v_add_f32_e32 v152, 1.0, v152
	v_rcp_f32_e32 v151, v151
	v_rcp_f32_e32 v152, v152
	v_add_f32_e32 v153, 1.0, v153
	v_rcp_f32_e32 v153, v153
	v_mul_f32_e32 v151, s101, v151
	v_mul_f32_e32 v152, s101, v152
	v_cvt_rpi_i32_f32_e32 v151, v151
	v_cvt_rpi_i32_f32_e32 v152, v152
	v_mul_f32_e32 v153, s101, v153
	v_lshl_or_b32 v151, v152, 8, v151
	v_mul_f32_e32 v152, s100, v18
	v_exp_f32_e32 v152, v152
	v_cvt_rpi_i32_f32_e32 v153, v153
	v_add_f32_e32 v152, 1.0, v152
	v_rcp_f32_e32 v152, v152
	v_min_u32_sdwa v153, v153, s81 dst_sel:BYTE_3 dst_unused:UNUSED_PAD src0_sel:DWORD src1_sel:DWORD
	v_mul_f32_e32 v152, s101, v152
	v_cvt_rpi_i32_f32_e32 v152, v152
	v_min_u32_sdwa v152, v152, s81 dst_sel:WORD_1 dst_unused:UNUSED_PAD src0_sel:DWORD src1_sel:DWORD
	s_nop 0
	v_or3_b32 v151, v151, v152, v153
	ds_write_b32 v150, v151 offset:24576
	v_mul_f32_e32 v151, s100, v12
	v_mul_f32_e32 v152, s100, v13
	v_exp_f32_e32 v151, v151
	v_exp_f32_e32 v152, v152
	v_mul_f32_e32 v153, s100, v15
	v_exp_f32_e32 v153, v153
	v_add_f32_e32 v151, 1.0, v151
	v_add_f32_e32 v152, 1.0, v152
	v_rcp_f32_e32 v151, v151
	v_rcp_f32_e32 v152, v152
	v_add_f32_e32 v153, 1.0, v153
	v_rcp_f32_e32 v153, v153
	v_mul_f32_e32 v151, s101, v151
	v_mul_f32_e32 v152, s101, v152
	v_cvt_rpi_i32_f32_e32 v151, v151
	v_cvt_rpi_i32_f32_e32 v152, v152
	v_mul_f32_e32 v153, s101, v153
	v_lshl_or_b32 v151, v152, 8, v151
	v_mul_f32_e32 v152, s100, v14
	v_exp_f32_e32 v152, v152
	v_cvt_rpi_i32_f32_e32 v153, v153
	v_add_f32_e32 v152, 1.0, v152
	v_rcp_f32_e32 v152, v152
	v_min_u32_sdwa v153, v153, s81 dst_sel:BYTE_3 dst_unused:UNUSED_PAD src0_sel:DWORD src1_sel:DWORD
	v_mul_f32_e32 v152, s101, v152
	v_cvt_rpi_i32_f32_e32 v152, v152
	v_min_u32_sdwa v152, v152, s81 dst_sel:WORD_1 dst_unused:UNUSED_PAD src0_sel:DWORD src1_sel:DWORD
	s_nop 0
	v_or3_b32 v151, v151, v152, v153
	ds_write_b32 v147, v151 offset:28672
	v_mul_f32_e32 v147, s100, v8
	v_mul_f32_e32 v151, s100, v9
	v_exp_f32_e32 v147, v147
	v_exp_f32_e32 v151, v151
	v_mul_f32_e32 v152, s100, v11
	v_exp_f32_e32 v152, v152
	v_add_f32_e32 v147, 1.0, v147
	v_add_f32_e32 v151, 1.0, v151
	v_rcp_f32_e32 v147, v147
	v_rcp_f32_e32 v151, v151
	v_add_f32_e32 v152, 1.0, v152
	v_rcp_f32_e32 v152, v152
	v_mul_f32_e32 v147, s101, v147
	v_mul_f32_e32 v151, s101, v151
	v_cvt_rpi_i32_f32_e32 v147, v147
	v_cvt_rpi_i32_f32_e32 v151, v151
	v_mul_f32_e32 v152, s101, v152
	v_lshl_or_b32 v147, v151, 8, v147
	v_mul_f32_e32 v151, s100, v10
	v_exp_f32_e32 v151, v151
	v_cvt_rpi_i32_f32_e32 v152, v152
	v_add_f32_e32 v151, 1.0, v151
	v_rcp_f32_e32 v151, v151
	v_min_u32_sdwa v152, v152, s81 dst_sel:BYTE_3 dst_unused:UNUSED_PAD src0_sel:DWORD src1_sel:DWORD
	v_mul_f32_e32 v151, s101, v151
	v_cvt_rpi_i32_f32_e32 v151, v151
	v_min_u32_sdwa v151, v151, s81 dst_sel:WORD_1 dst_unused:UNUSED_PAD src0_sel:DWORD src1_sel:DWORD
	s_nop 0
	v_or3_b32 v147, v147, v151, v152
	ds_write_b32 v148, v147 offset:28672
	v_mul_f32_e32 v147, s100, v4
	v_mul_f32_e32 v148, s100, v5
	v_exp_f32_e32 v147, v147
	v_exp_f32_e32 v148, v148
	v_mul_f32_e32 v151, s100, v7
	v_exp_f32_e32 v151, v151
	v_add_f32_e32 v147, 1.0, v147
	v_add_f32_e32 v148, 1.0, v148
	v_rcp_f32_e32 v147, v147
	v_rcp_f32_e32 v148, v148
	v_add_f32_e32 v151, 1.0, v151
	v_rcp_f32_e32 v151, v151
	v_mul_f32_e32 v147, s101, v147
	v_mul_f32_e32 v148, s101, v148
	v_cvt_rpi_i32_f32_e32 v147, v147
	v_cvt_rpi_i32_f32_e32 v148, v148
	v_mul_f32_e32 v151, s101, v151
	v_lshl_or_b32 v147, v148, 8, v147
	v_mul_f32_e32 v148, s100, v6
	v_exp_f32_e32 v148, v148
	v_cvt_rpi_i32_f32_e32 v151, v151
	v_add_f32_e32 v148, 1.0, v148
	v_rcp_f32_e32 v148, v148
	v_min_u32_sdwa v151, v151, s81 dst_sel:BYTE_3 dst_unused:UNUSED_PAD src0_sel:DWORD src1_sel:DWORD
	v_mul_f32_e32 v148, s101, v148
	v_cvt_rpi_i32_f32_e32 v148, v148
	v_min_u32_sdwa v148, v148, s81 dst_sel:WORD_1 dst_unused:UNUSED_PAD src0_sel:DWORD src1_sel:DWORD
	s_nop 0
	v_or3_b32 v147, v147, v148, v151
	ds_write_b32 v149, v147 offset:28672
	v_mul_f32_e32 v147, s100, v0
	v_mul_f32_e32 v148, s100, v1
	v_exp_f32_e32 v147, v147
	v_exp_f32_e32 v148, v148
	v_mul_f32_e32 v149, s100, v3
	v_exp_f32_e32 v149, v149
	v_add_f32_e32 v147, 1.0, v147
	v_add_f32_e32 v148, 1.0, v148
	v_rcp_f32_e32 v147, v147
	v_rcp_f32_e32 v148, v148
	v_add_f32_e32 v149, 1.0, v149
	v_rcp_f32_e32 v149, v149
	v_mul_f32_e32 v147, s101, v147
	v_mul_f32_e32 v148, s101, v148
	v_cvt_rpi_i32_f32_e32 v147, v147
	v_cvt_rpi_i32_f32_e32 v148, v148
	v_mul_f32_e32 v149, s101, v149
	v_lshl_or_b32 v147, v148, 8, v147
	v_mul_f32_e32 v148, s100, v2
	v_exp_f32_e32 v148, v148
	v_cvt_rpi_i32_f32_e32 v149, v149
	v_ashrrev_i32_e32 v151, 4, v145
	v_add_f32_e32 v148, 1.0, v148
	v_rcp_f32_e32 v148, v148
	v_min_u32_sdwa v149, v149, s81 dst_sel:BYTE_3 dst_unused:UNUSED_PAD src0_sel:DWORD src1_sel:DWORD
	v_mul_f32_e32 v148, s101, v148
	v_cvt_rpi_i32_f32_e32 v148, v148
	v_min_u32_sdwa v148, v148, s81 dst_sel:WORD_1 dst_unused:UNUSED_PAD src0_sel:DWORD src1_sel:DWORD
	s_nop 0
	v_or3_b32 v147, v147, v148, v149
	ds_write_b32 v150, v147 offset:28672
	v_and_b32_e32 v150, 0xf0, v146
	v_xor_b32_e32 v146, v151, v144
	v_lshlrev_b32_e32 v146, 4, v146
	v_and_b32_e32 v146, 0xf0, v146
	v_lshl_or_b32 v146, v151, 8, v146
	v_add_u32_e32 v146, 0x10000, v146
	s_waitcnt lgkmcnt(0)
	s_barrier
	s_waitcnt vmcnt(0)
	ds_read_b128 v[146:149], v146
	v_mad_u64_u32 v[152:153], s[34:35], v151, s33, v[150:151]
	s_waitcnt lgkmcnt(0)
	buffer_store_dwordx4 v[146:149], v152, s[16:19], 0 offen sc1
	s_nop 1
	v_add_u32_e32 v146, 0x200, v145
	v_ashrrev_i32_e32 v151, 4, v146
	v_xor_b32_e32 v146, v151, v144
	v_lshlrev_b32_e32 v146, 4, v146
	v_and_b32_e32 v146, 0xf0, v146
	v_lshl_or_b32 v146, v151, 8, v146
	v_add_u32_e32 v146, 0x10000, v146
	ds_read_b128 v[146:149], v146
	v_mad_u64_u32 v[152:153], s[34:35], v151, s33, v[150:151]
	s_waitcnt lgkmcnt(0)
	buffer_store_dwordx4 v[146:149], v152, s[16:19], 0 offen sc1
	s_nop 1
	v_add_u32_e32 v146, 0x400, v145
	v_ashrrev_i32_e32 v151, 4, v146
	v_xor_b32_e32 v146, v151, v144
	v_lshlrev_b32_e32 v146, 4, v146
	v_and_b32_e32 v146, 0xf0, v146
	v_lshl_or_b32 v146, v151, 8, v146
	v_add_u32_e32 v146, 0x10000, v146
	ds_read_b128 v[146:149], v146
	v_mad_u64_u32 v[152:153], s[34:35], v151, s33, v[150:151]
	s_waitcnt lgkmcnt(0)
	buffer_store_dwordx4 v[146:149], v152, s[16:19], 0 offen sc1
	s_nop 1
	v_add_u32_e32 v146, 0x600, v145
	v_ashrrev_i32_e32 v151, 4, v146
	v_xor_b32_e32 v146, v151, v144
	v_lshlrev_b32_e32 v146, 4, v146
	v_and_b32_e32 v146, 0xf0, v146
	v_lshl_or_b32 v146, v151, 8, v146
	v_add_u32_e32 v146, 0x10000, v146
	ds_read_b128 v[146:149], v146
	v_mad_u64_u32 v[152:153], s[34:35], v151, s33, v[150:151]
	s_waitcnt lgkmcnt(0)
	buffer_store_dwordx4 v[146:149], v152, s[16:19], 0 offen sc1
	s_nop 1
	v_add_u32_e32 v146, 0x800, v145
	v_ashrrev_i32_e32 v151, 4, v146
	v_xor_b32_e32 v146, v151, v144
	v_lshlrev_b32_e32 v146, 4, v146
	v_and_b32_e32 v146, 0xf0, v146
	v_lshl_or_b32 v146, v151, 8, v146
	v_add_u32_e32 v146, 0x10000, v146
	ds_read_b128 v[146:149], v146
	v_mad_u64_u32 v[152:153], s[34:35], v151, s33, v[150:151]
	s_waitcnt lgkmcnt(0)
	buffer_store_dwordx4 v[146:149], v152, s[16:19], 0 offen sc1
	s_nop 1
	v_add_u32_e32 v146, 0xa00, v145
	v_ashrrev_i32_e32 v151, 4, v146
	v_xor_b32_e32 v146, v151, v144
	v_lshlrev_b32_e32 v146, 4, v146
	v_and_b32_e32 v146, 0xf0, v146
	v_lshl_or_b32 v146, v151, 8, v146
	v_add_u32_e32 v146, 0x10000, v146
	ds_read_b128 v[146:149], v146
	v_mad_u64_u32 v[152:153], s[34:35], v151, s33, v[150:151]
	s_waitcnt lgkmcnt(0)
	buffer_store_dwordx4 v[146:149], v152, s[16:19], 0 offen sc1
	s_nop 1
	v_add_u32_e32 v146, 0xc00, v145
	v_ashrrev_i32_e32 v151, 4, v146
	v_xor_b32_e32 v146, v151, v144
	v_lshlrev_b32_e32 v146, 4, v146
	v_and_b32_e32 v146, 0xf0, v146
	v_lshl_or_b32 v146, v151, 8, v146
	v_add_u32_e32 v146, 0x10000, v146
	ds_read_b128 v[146:149], v146
	v_mad_u64_u32 v[152:153], s[34:35], v151, s33, v[150:151]
	v_add_u32_e32 v145, 0xe00, v145
	s_waitcnt lgkmcnt(0)
	buffer_store_dwordx4 v[146:149], v152, s[16:19], 0 offen sc1
	s_nop 1
	v_ashrrev_i32_e32 v148, 4, v145
	v_xor_b32_e32 v144, v148, v144
	v_lshlrev_b32_e32 v144, 4, v144
	v_and_b32_e32 v144, 0xf0, v144
	v_lshl_or_b32 v144, v148, 8, v144
	v_add_u32_e32 v144, 0x10000, v144
	ds_read_b128 v[144:147], v144
	v_mad_u64_u32 v[148:149], s[34:35], v148, s33, v[150:151]
	s_mov_b64 s[34:35], 0
	s_waitcnt lgkmcnt(0)
	buffer_store_dwordx4 v[144:147], v148, s[16:19], 0 offen sc1
	s_waitcnt lgkmcnt(0)
	s_barrier

.LBB0_457:
	s_mov_b32 s100, 0xbfb8aa3b
	s_mov_b32 s101, 0x437f0000
	v_mov_b32_e32 v156, v194
	v_mov_b32_e32 v157, v165
	v_mov_b32_e32 v158, v195
	v_mov_b32_e32 v159, v193
	v_lshlrev_b32_e32 v202, 16, v142
	v_lshlrev_b32_e32 v144, 4, v158
	v_lshl_add_u32 v144, v159, 2, v144
	v_ashrrev_i32_e32 v145, 31, v144
	v_lshlrev_b64 v[148:149], 2, v[144:145]
	v_lshl_add_u64 v[152:153], s[66:67], 0, v[148:149]
	v_lshl_add_u64 v[154:155], s[64:65], 0, v[148:149]
	global_load_dwordx4 v[144:147], v[152:153], off
	global_load_dwordx4 v[148:151], v[154:155], off
	v_and_b32_e32 v246, 63, v163
	v_lshlrev_b32_e32 v246, 2, v246
	global_load_dword v247, v246, s[68:69] offset:256
	global_load_dword v246, v246, s[68:69]
	v_and_b32_e32 v203, 0xffff0000, v142
	v_lshlrev_b32_e32 v142, 6, v158
	v_lshl_add_u32 v158, v158, 2, v159
	v_lshlrev_b32_e32 v160, 15, v156
	v_lshl_add_u32 v142, v156, 8, v142
	v_xor_b32_e32 v156, v158, v157
	v_lshl_or_b32 v201, v159, 4, v142
	v_lshlrev_b32_e32 v142, 4, v156
	v_lshlrev_b32_e32 v198, 8, v157
	v_add3_u32 v142, v142, v160, s89
	v_add_u32_e32 v158, v142, v198
	v_lshlrev_b32_e32 v196, 16, v140
	v_and_b32_e32 v197, 0xffff0000, v140
	v_lshlrev_b32_e32 v140, 16, v141
	v_and_b32_e32 v141, 0xffff0000, v141
	v_or_b32_e32 v156, v201, v157
	s_movk_i32 s4, 0x100
	v_add_u32_e32 v200, 0x100, v156
	v_cmp_gt_i32_e64 s[4:5], s4, v156
	s_and_b32 s9, s9, 0xffff
	v_cmp_lt_i32_e32 vcc, s81, v156
	s_waitcnt vmcnt(0)
	v_add_f32_e32 v142, v124, v144
	v_add_f32_e32 v159, v120, v148
	v_add_f32_e32 v160, v125, v145
	v_add_f32_e32 v198, v121, v149
	v_add_f32_e32 v199, v126, v146
	v_add_f32_e32 v204, v122, v150
	v_add_f32_e32 v205, v127, v147
	v_add_f32_e32 v206, v123, v151
	v_med3_f32 v142, v142, s6, v191
	v_med3_f32 v159, v159, s6, v191
	v_med3_f32 v160, v160, s6, v191
	v_med3_f32 v198, v198, s6, v191
	v_med3_f32 v199, v199, s6, v191
	v_med3_f32 v204, v204, s6, v191
	v_med3_f32 v205, v205, s6, v191
	v_med3_f32 v206, v206, s6, v191
	v_mul_f32_e32 v142, s100, v142
	v_mul_f32_e32 v159, s100, v159
	v_mul_f32_e32 v160, s100, v160
	v_mul_f32_e32 v207, s100, v198
	v_mul_f32_e32 v208, s100, v199
	v_mul_f32_e32 v209, s100, v204
	v_mul_f32_e32 v205, s100, v205
	v_mul_f32_e32 v206, s100, v206
	v_exp_f32_e32 v198, v142
	v_exp_f32_e32 v142, v159
	v_exp_f32_e32 v199, v160
	v_exp_f32_e32 v159, v207
	v_exp_f32_e32 v204, v208
	v_exp_f32_e32 v160, v209
	v_exp_f32_e32 v205, v205
	v_exp_f32_e32 v206, v206
	v_add_f32_e32 v142, 1.0, v142
	v_add_f32_e32 v159, 1.0, v159
	v_pk_add_f32 v[198:199], v[198:199], 1.0 op_sel_hi:[1,0]
	v_add_f32_e32 v160, 1.0, v160
	v_add_f32_e32 v211, 1.0, v206
	v_pk_add_f32 v[204:205], v[204:205], 1.0 op_sel_hi:[1,0]
	v_mul_f32_e32 v206, v198, v142
	v_mul_f32_e32 v207, v199, v159
	v_mul_f32_e32 v208, v204, v160
	v_mul_f32_e32 v209, v205, v211
	v_rcp_f32_e32 v206, v206
	v_rcp_f32_e32 v207, v207
	v_rcp_f32_e32 v208, v208
	v_rcp_f32_e32 v209, v209
	v_mul_f32_e32 v142, v142, v206
	v_pk_mul_f32 v[198:199], v[198:199], v[206:207]
	v_mul_f32_e32 v160, v160, v208
	v_pk_mul_f32 v[204:205], v[204:205], v[208:209]
	v_mul_f32_e32 v206, v211, v209
	v_pk_mul_f32 v[196:197], v[198:199], v[196:197]
	v_mul_f32_e32 v160, s101, v160
	v_pk_mul_f32 v[140:141], v[204:205], v[140:141]
	v_mul_f32_e32 v198, s101, v206
	v_rndne_f32_e32 v160, v160
	v_cvt_pk_f16_f32 v140, v140, v141
	v_rndne_f32_e32 v141, v198
	v_cvt_f16_f32_e32 v141, v141
	v_cvt_f16_f32_e32 v160, v160
	v_mul_f32_e32 v159, v159, v207
	v_mul_f32_e32 v159, s101, v159
	v_bfi_b32 v199, s98, v141, v140
	v_pack_b32_f16 v198, v160, v140
	v_add_f32_e32 v140, v104, v148
	v_rndne_f32_e32 v159, v159
	v_med3_f32 v140, v140, s6, v191
	v_mul_f32_e32 v140, s100, v140
	v_cvt_f16_f32_e32 v159, v159
	v_exp_f32_e32 v141, v140
	v_mul_f32_e32 v142, s101, v142
	v_rndne_f32_e32 v142, v142
	v_cvt_pk_f16_f32 v196, v196, v197
	v_add_f32_e32 v210, v108, v144
	v_bfi_b32 v197, s98, v159, v196
	v_add_f32_e32 v159, 1.0, v141
	v_add_f32_e32 v141, v109, v145
	v_cvt_f16_f32_e32 v142, v142
	v_med3_f32 v140, v210, s6, v191
	v_med3_f32 v141, v141, s6, v191
	v_mul_f32_e32 v140, s100, v140
	v_mul_f32_e32 v141, s100, v141
	v_exp_f32_e32 v140, v140
	v_exp_f32_e32 v141, v141
	v_pack_b32_f16 v196, v142, v196
	v_add_f32_e32 v142, v105, v149
	v_med3_f32 v142, v142, s6, v191
	v_mul_f32_e32 v142, s100, v142
	v_pk_add_f32 v[140:141], v[140:141], 1.0 op_sel_hi:[1,0]
	v_exp_f32_e32 v160, v142
	v_mul_f32_e32 v142, v140, v159
	v_rcp_f32_e32 v142, v142
	ds_write_b128 v158, v[196:199]
	v_lshlrev_b32_e32 v196, 16, v143
	v_and_b32_e32 v197, 0xffff0000, v143
	v_add_f32_e32 v160, 1.0, v160
	v_mul_f32_e32 v143, v159, v142
	v_mul_f32_e32 v159, s101, v143
	v_mul_f32_e32 v143, v141, v160
	v_rcp_f32_e32 v143, v143
	v_rndne_f32_e32 v159, v159
	v_cvt_f16_f32_e32 v159, v159
	v_pk_mul_f32 v[140:141], v[140:141], v[142:143]
	v_add_f32_e32 v142, v107, v151
	v_pk_mul_f32 v[140:141], v[140:141], v[202:203]
	v_med3_f32 v142, v142, s6, v191
	v_cvt_pk_f16_f32 v198, v140, v141
	v_add_f32_e32 v141, v106, v150
	v_med3_f32 v141, v141, s6, v191
	v_mul_f32_e32 v141, s100, v141
	v_exp_f32_e32 v141, v141
	v_mul_f32_e32 v140, v160, v143
	v_mul_f32_e32 v140, s101, v140
	v_rndne_f32_e32 v143, v140
	v_add_f32_e32 v140, v110, v146
	v_add_f32_e32 v160, 1.0, v141
	v_add_f32_e32 v141, v111, v147
	v_med3_f32 v140, v140, s6, v191
	v_med3_f32 v141, v141, s6, v191
	v_mul_f32_e32 v140, s100, v140
	v_mul_f32_e32 v141, s100, v141
	v_exp_f32_e32 v140, v140
	v_exp_f32_e32 v141, v141
	v_mul_f32_e32 v142, s100, v142
	v_exp_f32_e32 v199, v142
	v_pk_add_f32 v[140:141], v[140:141], 1.0 op_sel_hi:[1,0]
	v_cvt_f16_f32_e32 v202, v143
	v_mul_f32_e32 v142, v140, v160
	v_rcp_f32_e32 v142, v142
	v_add_f32_e32 v199, 1.0, v199
	v_mul_f32_e32 v143, v160, v142
	v_mul_f32_e32 v160, s101, v143
	v_mul_f32_e32 v143, v141, v199
	v_rcp_f32_e32 v143, v143
	v_rndne_f32_e32 v160, v160
	v_cvt_f16_f32_e32 v160, v160
	v_mul_f32_e32 v199, v199, v143
	v_mul_f32_e32 v199, s101, v199
	v_rndne_f32_e32 v199, v199
	v_cvt_f16_f32_e32 v199, v199
	v_pk_mul_f32 v[140:141], v[140:141], v[142:143]
	s_nop 0
	v_pk_mul_f32 v[140:141], v[140:141], v[196:197]
	v_lshlrev_b32_e32 v196, 16, v137
	v_cvt_pk_f16_f32 v140, v140, v141
	v_bfi_b32 v143, s98, v199, v140
	v_bfi_b32 v141, s98, v202, v198
	v_pack_b32_f16 v142, v160, v140
	v_pack_b32_f16 v140, v159, v198
	ds_write_b128 v158, v[140:143] offset:4096
	v_add_f32_e32 v142, v88, v148
	v_lshlrev_b32_e32 v140, 16, v136
	v_and_b32_e32 v141, 0xffff0000, v136
	v_add_f32_e32 v136, v92, v144
	v_med3_f32 v142, v142, s6, v191
	v_mul_f32_e32 v142, s100, v142
	v_med3_f32 v136, v136, s6, v191
	v_exp_f32_e32 v143, v142
	v_mul_f32_e32 v136, s100, v136
	v_exp_f32_e32 v142, v136
	v_add_f32_e32 v136, v93, v145
	v_med3_f32 v136, v136, s6, v191
	v_mul_f32_e32 v136, s100, v136
	v_add_f32_e32 v159, 1.0, v143
	v_exp_f32_e32 v143, v136
	v_add_f32_e32 v160, v89, v149
	v_med3_f32 v136, v160, s6, v191
	v_mul_f32_e32 v136, s100, v136
	v_pk_add_f32 v[142:143], v[142:143], 1.0 op_sel_hi:[1,0]
	v_exp_f32_e32 v160, v136
	v_mul_f32_e32 v136, v142, v159
	v_rcp_f32_e32 v136, v136
	v_and_b32_e32 v197, 0xffff0000, v137
	v_add_f32_e32 v160, 1.0, v160
	v_mul_f32_e32 v137, v159, v136
	v_mul_f32_e32 v159, s101, v137
	v_mul_f32_e32 v137, v143, v160
	v_rcp_f32_e32 v137, v137
	v_rndne_f32_e32 v159, v159
	v_cvt_f16_f32_e32 v159, v159
	v_pk_mul_f32 v[142:143], v[142:143], v[136:137]
	v_mul_f32_e32 v136, v160, v137
	v_add_f32_e32 v137, v90, v150
	v_med3_f32 v137, v137, s6, v191
	v_mul_f32_e32 v137, s100, v137
	v_exp_f32_e32 v137, v137
	v_pk_mul_f32 v[140:141], v[142:143], v[140:141]
	v_mul_f32_e32 v136, s101, v136
	v_cvt_pk_f16_f32 v198, v140, v141
	v_rndne_f32_e32 v141, v136
	v_add_f32_e32 v136, v94, v146
	v_add_f32_e32 v142, 1.0, v137
	v_add_f32_e32 v137, v95, v147
	v_med3_f32 v136, v136, s6, v191
	v_med3_f32 v137, v137, s6, v191
	v_mul_f32_e32 v136, s100, v136
	v_mul_f32_e32 v137, s100, v137
	v_exp_f32_e32 v136, v136
	v_exp_f32_e32 v137, v137
	v_add_f32_e32 v140, v91, v151
	v_med3_f32 v140, v140, s6, v191
	v_mul_f32_e32 v140, s100, v140
	v_pk_add_f32 v[136:137], v[136:137], 1.0 op_sel_hi:[1,0]
	v_exp_f32_e32 v143, v140
	v_mul_f32_e32 v140, v136, v142
	v_rcp_f32_e32 v140, v140
	v_cvt_f16_f32_e32 v160, v141
	v_add_f32_e32 v143, 1.0, v143
	v_mul_f32_e32 v141, v142, v140
	v_mul_f32_e32 v142, s101, v141
	v_mul_f32_e32 v141, v137, v143
	v_rcp_f32_e32 v141, v141
	v_rndne_f32_e32 v142, v142
	v_cvt_f16_f32_e32 v142, v142
	v_mul_f32_e32 v143, v143, v141
	v_mul_f32_e32 v143, s101, v143
	v_rndne_f32_e32 v143, v143
	v_cvt_f16_f32_e32 v143, v143
	v_pk_mul_f32 v[136:137], v[136:137], v[140:141]
	v_bfi_b32 v141, s98, v160, v198
	v_pk_mul_f32 v[136:137], v[136:137], v[196:197]
	v_pack_b32_f16 v140, v159, v198
	v_cvt_pk_f16_f32 v136, v136, v137
	v_bfi_b32 v143, s98, v143, v136
	v_pack_b32_f16 v142, v142, v136
	ds_write_b128 v158, v[140:143] offset:8192
	v_add_f32_e32 v140, v72, v148
	v_lshlrev_b32_e32 v136, 16, v138
	v_and_b32_e32 v137, 0xffff0000, v138
	v_add_f32_e32 v138, v76, v144
	v_med3_f32 v140, v140, s6, v191
	v_mul_f32_e32 v140, s100, v140
	v_med3_f32 v138, v138, s6, v191
	v_exp_f32_e32 v141, v140
	v_mul_f32_e32 v138, s100, v138
	v_exp_f32_e32 v140, v138
	v_add_f32_e32 v138, v77, v145
	v_med3_f32 v138, v138, s6, v191
	v_mul_f32_e32 v138, s100, v138
	v_add_f32_e32 v159, 1.0, v141
	v_exp_f32_e32 v141, v138
	v_add_f32_e32 v142, v73, v149
	v_med3_f32 v138, v142, s6, v191
	v_mul_f32_e32 v138, s100, v138
	v_pk_add_f32 v[140:141], v[140:141], 1.0 op_sel_hi:[1,0]
	v_exp_f32_e32 v160, v138
	v_mul_f32_e32 v138, v140, v159
	v_rcp_f32_e32 v138, v138
	v_lshlrev_b32_e32 v142, 16, v139
	v_and_b32_e32 v143, 0xffff0000, v139
	v_add_f32_e32 v160, 1.0, v160
	v_mul_f32_e32 v139, v159, v138
	v_mul_f32_e32 v159, s101, v139
	v_mul_f32_e32 v139, v141, v160
	v_rcp_f32_e32 v139, v139
	v_rndne_f32_e32 v159, v159
	v_cvt_f16_f32_e32 v159, v159
	v_pk_mul_f32 v[140:141], v[140:141], v[138:139]
	v_add_f32_e32 v138, v75, v151
	v_pk_mul_f32 v[136:137], v[140:141], v[136:137]
	v_med3_f32 v138, v138, s6, v191
	v_cvt_pk_f16_f32 v140, v136, v137
	v_add_f32_e32 v137, v74, v150
	v_med3_f32 v137, v137, s6, v191
	v_mul_f32_e32 v137, s100, v137
	v_exp_f32_e32 v137, v137
	v_mul_f32_e32 v136, v160, v139
	v_mul_f32_e32 v136, s101, v136
	v_rndne_f32_e32 v139, v136
	v_add_f32_e32 v136, v78, v146
	v_add_f32_e32 v141, 1.0, v137
	v_add_f32_e32 v137, v79, v147
	v_med3_f32 v136, v136, s6, v191
	v_med3_f32 v137, v137, s6, v191
	v_mul_f32_e32 v136, s100, v136
	v_mul_f32_e32 v137, s100, v137
	v_exp_f32_e32 v136, v136
	v_exp_f32_e32 v137, v137
	v_mul_f32_e32 v138, s100, v138
	v_exp_f32_e32 v160, v138
	v_pk_add_f32 v[136:137], v[136:137], 1.0 op_sel_hi:[1,0]
	v_cvt_f16_f32_e32 v196, v139
	v_mul_f32_e32 v138, v136, v141
	v_rcp_f32_e32 v138, v138
	v_add_f32_e32 v160, 1.0, v160
	v_mul_f32_e32 v139, v141, v138
	v_mul_f32_e32 v141, s101, v139
	v_mul_f32_e32 v139, v137, v160
	v_rcp_f32_e32 v139, v139
	v_rndne_f32_e32 v141, v141
	v_cvt_f16_f32_e32 v141, v141
	v_mul_f32_e32 v160, v160, v139
	v_mul_f32_e32 v160, s101, v160
	v_rndne_f32_e32 v160, v160
	v_cvt_f16_f32_e32 v160, v160
	v_pk_mul_f32 v[136:137], v[136:137], v[138:139]
	s_nop 0
	v_pk_mul_f32 v[136:137], v[136:137], v[142:143]
	s_nop 0
	v_cvt_pk_f16_f32 v136, v136, v137
	v_bfi_b32 v139, s98, v160, v136
	v_bfi_b32 v137, s98, v196, v140
	v_pack_b32_f16 v138, v141, v136
	v_pack_b32_f16 v136, v159, v140
	ds_write_b128 v158, v[136:139] offset:12288
	v_add_f32_e32 v138, v56, v148
	v_lshlrev_b32_e32 v136, 16, v132
	v_and_b32_e32 v137, 0xffff0000, v132
	v_add_f32_e32 v132, v60, v144
	v_med3_f32 v138, v138, s6, v191
	v_mul_f32_e32 v138, s100, v138
	v_med3_f32 v132, v132, s6, v191
	v_exp_f32_e32 v139, v138
	v_mul_f32_e32 v132, s100, v132
	v_exp_f32_e32 v138, v132
	v_add_f32_e32 v132, v61, v145
	v_med3_f32 v132, v132, s6, v191
	v_mul_f32_e32 v132, s100, v132
	v_add_f32_e32 v142, 1.0, v139
	v_exp_f32_e32 v139, v132
	v_add_f32_e32 v140, v57, v149
	v_med3_f32 v132, v140, s6, v191
	v_mul_f32_e32 v132, s100, v132
	v_pk_add_f32 v[138:139], v[138:139], 1.0 op_sel_hi:[1,0]
	v_exp_f32_e32 v143, v132
	v_mul_f32_e32 v132, v138, v142
	v_rcp_f32_e32 v132, v132
	v_lshlrev_b32_e32 v140, 16, v133
	v_and_b32_e32 v141, 0xffff0000, v133
	v_add_f32_e32 v143, 1.0, v143
	v_mul_f32_e32 v133, v142, v132
	v_mul_f32_e32 v142, s101, v133
	v_mul_f32_e32 v133, v139, v143
	v_rcp_f32_e32 v133, v133
	v_rndne_f32_e32 v142, v142
	v_cvt_f16_f32_e32 v142, v142
	v_pk_mul_f32 v[138:139], v[138:139], v[132:133]
	v_mul_f32_e32 v132, v143, v133
	v_add_f32_e32 v133, v58, v150
	v_med3_f32 v133, v133, s6, v191
	v_mul_f32_e32 v133, s100, v133
	v_exp_f32_e32 v133, v133
	v_pk_mul_f32 v[136:137], v[138:139], v[136:137]
	v_mul_f32_e32 v132, s101, v132
	v_cvt_pk_f16_f32 v159, v136, v137
	v_rndne_f32_e32 v137, v132
	v_add_f32_e32 v132, v62, v146
	v_add_f32_e32 v138, 1.0, v133
	v_add_f32_e32 v133, v63, v147
	v_med3_f32 v132, v132, s6, v191
	v_med3_f32 v133, v133, s6, v191
	v_mul_f32_e32 v132, s100, v132
	v_mul_f32_e32 v133, s100, v133
	v_exp_f32_e32 v132, v132
	v_exp_f32_e32 v133, v133
	v_add_f32_e32 v136, v59, v151
	v_med3_f32 v136, v136, s6, v191
	v_mul_f32_e32 v136, s100, v136
	v_pk_add_f32 v[132:133], v[132:133], 1.0 op_sel_hi:[1,0]
	v_exp_f32_e32 v139, v136
	v_mul_f32_e32 v136, v132, v138
	v_rcp_f32_e32 v136, v136
	v_cvt_f16_f32_e32 v143, v137
	v_add_f32_e32 v139, 1.0, v139
	v_mul_f32_e32 v137, v138, v136
	v_mul_f32_e32 v138, s101, v137
	v_mul_f32_e32 v137, v133, v139
	v_rcp_f32_e32 v137, v137
	v_rndne_f32_e32 v138, v138
	v_cvt_f16_f32_e32 v138, v138
	v_mul_f32_e32 v139, v139, v137
	v_mul_f32_e32 v139, s101, v139
	v_rndne_f32_e32 v139, v139
	v_cvt_f16_f32_e32 v139, v139
	v_pk_mul_f32 v[132:133], v[132:133], v[136:137]
	v_bfi_b32 v137, s98, v143, v159
	v_pk_mul_f32 v[132:133], v[132:133], v[140:141]
	v_pack_b32_f16 v136, v142, v159
	v_cvt_pk_f16_f32 v132, v132, v133
	v_bfi_b32 v139, s98, v139, v132
	v_pack_b32_f16 v138, v138, v132
	ds_write_b128 v158, v[136:139] offset:16384
	v_add_f32_e32 v136, v40, v148
	v_lshlrev_b32_e32 v132, 16, v134
	v_and_b32_e32 v133, 0xffff0000, v134
	v_add_f32_e32 v134, v44, v144
	v_med3_f32 v136, v136, s6, v191
	v_mul_f32_e32 v136, s100, v136
	v_med3_f32 v134, v134, s6, v191
	v_exp_f32_e32 v137, v136
	v_mul_f32_e32 v134, s100, v134
	v_exp_f32_e32 v136, v134
	v_add_f32_e32 v134, v45, v145
	v_med3_f32 v134, v134, s6, v191
	v_mul_f32_e32 v134, s100, v134
	v_add_f32_e32 v140, 1.0, v137
	v_exp_f32_e32 v137, v134
	v_add_f32_e32 v138, v41, v149
	v_med3_f32 v134, v138, s6, v191
	v_mul_f32_e32 v134, s100, v134
	v_pk_add_f32 v[136:137], v[136:137], 1.0 op_sel_hi:[1,0]
	v_exp_f32_e32 v141, v134
	v_mul_f32_e32 v134, v136, v140
	v_rcp_f32_e32 v134, v134
	v_lshlrev_b32_e32 v138, 16, v135
	v_and_b32_e32 v139, 0xffff0000, v135
	v_add_f32_e32 v141, 1.0, v141
	v_mul_f32_e32 v135, v140, v134
	v_mul_f32_e32 v140, s101, v135
	v_mul_f32_e32 v135, v137, v141
	v_rcp_f32_e32 v135, v135
	v_rndne_f32_e32 v140, v140
	v_cvt_f16_f32_e32 v140, v140
	v_pk_mul_f32 v[136:137], v[136:137], v[134:135]
	v_add_f32_e32 v134, v43, v151
	v_pk_mul_f32 v[132:133], v[136:137], v[132:133]
	v_med3_f32 v134, v134, s6, v191
	v_cvt_pk_f16_f32 v136, v132, v133
	v_add_f32_e32 v133, v42, v150
	v_med3_f32 v133, v133, s6, v191
	v_mul_f32_e32 v133, s100, v133
	v_exp_f32_e32 v133, v133
	v_mul_f32_e32 v132, v141, v135
	v_mul_f32_e32 v132, s101, v132
	v_rndne_f32_e32 v135, v132
	v_add_f32_e32 v132, v46, v146
	v_add_f32_e32 v137, 1.0, v133
	v_add_f32_e32 v133, v47, v147
	v_med3_f32 v132, v132, s6, v191
	v_med3_f32 v133, v133, s6, v191
	v_mul_f32_e32 v132, s100, v132
	v_mul_f32_e32 v133, s100, v133
	v_exp_f32_e32 v132, v132
	v_exp_f32_e32 v133, v133
	v_mul_f32_e32 v134, s100, v134
	v_exp_f32_e32 v141, v134
	v_pk_add_f32 v[132:133], v[132:133], 1.0 op_sel_hi:[1,0]
	v_cvt_f16_f32_e32 v142, v135
	v_mul_f32_e32 v134, v132, v137
	v_rcp_f32_e32 v134, v134
	v_add_f32_e32 v141, 1.0, v141
	v_mul_f32_e32 v135, v137, v134
	v_mul_f32_e32 v137, s101, v135
	v_mul_f32_e32 v135, v133, v141
	v_rcp_f32_e32 v135, v135
	v_rndne_f32_e32 v137, v137
	v_cvt_f16_f32_e32 v137, v137
	v_mul_f32_e32 v141, v141, v135
	v_mul_f32_e32 v141, s101, v141
	v_rndne_f32_e32 v141, v141
	v_cvt_f16_f32_e32 v141, v141
	v_pk_mul_f32 v[132:133], v[132:133], v[134:135]
	s_nop 0
	v_pk_mul_f32 v[132:133], v[132:133], v[138:139]
	s_nop 0
	v_cvt_pk_f16_f32 v132, v132, v133
	v_bfi_b32 v135, s98, v141, v132
	v_bfi_b32 v133, s98, v142, v136
	v_pack_b32_f16 v134, v137, v132
	v_pack_b32_f16 v132, v140, v136
	ds_write_b128 v158, v[132:135] offset:20480
	v_add_f32_e32 v134, v24, v148
	v_lshlrev_b32_e32 v132, 16, v128
	v_and_b32_e32 v133, 0xffff0000, v128
	v_add_f32_e32 v128, v28, v144
	v_med3_f32 v134, v134, s6, v191
	v_mul_f32_e32 v134, s100, v134
	v_med3_f32 v128, v128, s6, v191
	v_exp_f32_e32 v135, v134
	v_mul_f32_e32 v128, s100, v128
	v_exp_f32_e32 v134, v128
	v_add_f32_e32 v128, v29, v145
	v_med3_f32 v128, v128, s6, v191
	v_mul_f32_e32 v128, s100, v128
	v_add_f32_e32 v138, 1.0, v135
	v_exp_f32_e32 v135, v128
	v_add_f32_e32 v136, v25, v149
	v_med3_f32 v128, v136, s6, v191
	v_mul_f32_e32 v128, s100, v128
	v_pk_add_f32 v[134:135], v[134:135], 1.0 op_sel_hi:[1,0]
	v_exp_f32_e32 v139, v128
	v_mul_f32_e32 v128, v134, v138
	v_rcp_f32_e32 v128, v128
	v_lshlrev_b32_e32 v136, 16, v129
	v_and_b32_e32 v137, 0xffff0000, v129
	v_add_f32_e32 v139, 1.0, v139
	v_mul_f32_e32 v129, v138, v128
	v_mul_f32_e32 v138, s101, v129
	v_mul_f32_e32 v129, v135, v139
	v_rcp_f32_e32 v129, v129
	v_rndne_f32_e32 v138, v138
	v_cvt_f16_f32_e32 v138, v138
	v_pk_mul_f32 v[134:135], v[134:135], v[128:129]
	v_mul_f32_e32 v128, v139, v129
	v_add_f32_e32 v129, v26, v150
	v_med3_f32 v129, v129, s6, v191
	v_mul_f32_e32 v129, s100, v129
	v_exp_f32_e32 v129, v129
	v_pk_mul_f32 v[132:133], v[134:135], v[132:133]
	v_mul_f32_e32 v128, s101, v128
	v_cvt_pk_f16_f32 v140, v132, v133
	v_rndne_f32_e32 v133, v128
	v_add_f32_e32 v128, v30, v146
	v_add_f32_e32 v134, 1.0, v129
	v_add_f32_e32 v129, v31, v147
	v_med3_f32 v128, v128, s6, v191
	v_med3_f32 v129, v129, s6, v191
	v_mul_f32_e32 v128, s100, v128
	v_mul_f32_e32 v129, s100, v129
	v_exp_f32_e32 v128, v128
	v_exp_f32_e32 v129, v129
	v_add_f32_e32 v132, v27, v151
	v_med3_f32 v132, v132, s6, v191
	v_mul_f32_e32 v132, s100, v132
	v_pk_add_f32 v[128:129], v[128:129], 1.0 op_sel_hi:[1,0]
	v_exp_f32_e32 v135, v132
	v_mul_f32_e32 v132, v128, v134
	v_rcp_f32_e32 v132, v132
	v_cvt_f16_f32_e32 v139, v133
	v_add_f32_e32 v135, 1.0, v135
	v_mul_f32_e32 v133, v134, v132
	v_mul_f32_e32 v134, s101, v133
	v_mul_f32_e32 v133, v129, v135
	v_rcp_f32_e32 v133, v133
	v_rndne_f32_e32 v134, v134
	v_cvt_f16_f32_e32 v134, v134
	v_mul_f32_e32 v135, v135, v133
	v_mul_f32_e32 v135, s101, v135
	v_rndne_f32_e32 v135, v135
	v_cvt_f16_f32_e32 v135, v135
	v_pk_mul_f32 v[128:129], v[128:129], v[132:133]
	v_bfi_b32 v133, s98, v139, v140
	v_pk_mul_f32 v[128:129], v[128:129], v[136:137]
	v_pack_b32_f16 v132, v138, v140
	v_cvt_pk_f16_f32 v128, v128, v129
	v_bfi_b32 v135, s98, v135, v128
	v_pack_b32_f16 v134, v134, v128
	ds_write_b128 v158, v[132:135] offset:24576
	v_add_f32_e32 v132, v8, v148
	v_lshlrev_b32_e32 v128, 16, v130
	v_and_b32_e32 v129, 0xffff0000, v130
	v_add_f32_e32 v130, v12, v144
	v_med3_f32 v132, v132, s6, v191
	v_mul_f32_e32 v132, s100, v132
	v_med3_f32 v130, v130, s6, v191
	v_exp_f32_e32 v133, v132
	v_mul_f32_e32 v130, s100, v130
	v_exp_f32_e32 v132, v130
	v_add_f32_e32 v130, v13, v145
	v_med3_f32 v130, v130, s6, v191
	v_mul_f32_e32 v130, s100, v130
	v_add_f32_e32 v136, 1.0, v133
	v_exp_f32_e32 v133, v130
	v_add_f32_e32 v134, v9, v149
	v_med3_f32 v130, v134, s6, v191
	v_mul_f32_e32 v130, s100, v130
	v_pk_add_f32 v[132:133], v[132:133], 1.0 op_sel_hi:[1,0]
	v_exp_f32_e32 v137, v130
	v_mul_f32_e32 v130, v132, v136
	v_rcp_f32_e32 v130, v130
	v_lshlrev_b32_e32 v134, 16, v131
	v_and_b32_e32 v135, 0xffff0000, v131
	v_add_f32_e32 v137, 1.0, v137
	v_mul_f32_e32 v131, v136, v130
	v_mul_f32_e32 v136, s101, v131
	v_mul_f32_e32 v131, v133, v137
	v_rcp_f32_e32 v131, v131
	v_rndne_f32_e32 v136, v136
	v_cvt_f16_f32_e32 v136, v136
	v_pk_mul_f32 v[132:133], v[132:133], v[130:131]
	v_add_f32_e32 v130, v11, v151
	v_pk_mul_f32 v[128:129], v[132:133], v[128:129]
	v_med3_f32 v130, v130, s6, v191
	v_cvt_pk_f16_f32 v132, v128, v129
	v_add_f32_e32 v129, v10, v150
	v_med3_f32 v129, v129, s6, v191
	v_mul_f32_e32 v129, s100, v129
	v_exp_f32_e32 v129, v129
	v_mul_f32_e32 v128, v137, v131
	v_mul_f32_e32 v128, s101, v128
	v_rndne_f32_e32 v131, v128
	v_add_f32_e32 v128, v14, v146
	v_add_f32_e32 v133, 1.0, v129
	v_add_f32_e32 v129, v15, v147
	v_med3_f32 v128, v128, s6, v191
	v_med3_f32 v129, v129, s6, v191
	v_mul_f32_e32 v128, s100, v128
	v_mul_f32_e32 v129, s100, v129
	v_exp_f32_e32 v128, v128
	v_exp_f32_e32 v129, v129
	v_mul_f32_e32 v130, s100, v130
	v_exp_f32_e32 v137, v130
	v_pk_add_f32 v[128:129], v[128:129], 1.0 op_sel_hi:[1,0]
	v_cvt_f16_f32_e32 v138, v131
	v_mul_f32_e32 v130, v128, v133
	v_rcp_f32_e32 v130, v130
	v_add_f32_e32 v137, 1.0, v137
	v_mul_f32_e32 v131, v133, v130
	v_mul_f32_e32 v133, s101, v131
	v_mul_f32_e32 v131, v129, v137
	v_rcp_f32_e32 v131, v131
	v_rndne_f32_e32 v133, v133
	v_cvt_f16_f32_e32 v133, v133
	v_mul_f32_e32 v137, v137, v131
	v_mul_f32_e32 v137, s101, v137
	v_rndne_f32_e32 v137, v137
	v_cvt_f16_f32_e32 v137, v137
	v_pk_mul_f32 v[128:129], v[128:129], v[130:131]
	s_nop 0
	v_pk_mul_f32 v[128:129], v[128:129], v[134:135]
	s_nop 0
	v_cvt_pk_f16_f32 v128, v128, v129
	v_bfi_b32 v131, s98, v137, v128
	v_bfi_b32 v129, s98, v138, v132
	v_pack_b32_f16 v130, v133, v128
	v_pack_b32_f16 v128, v136, v132
	ds_write_b128 v158, v[128:131] offset:28672
	v_cndmask_b32_e64 v128, v200, v156, s[4:5]
	v_and_b32_e32 v140, 7, v128
	v_ashrrev_i32_e32 v136, 3, v128
	v_lshlrev_b32_e32 v133, 1, v140
	v_lshl_add_u32 v132, v136, 8, v192
	v_bitop3_b32 v128, v133, v136, 15 bitop3:0x78
	v_lshl_or_b32 v128, v128, 4, v132
	s_waitcnt lgkmcnt(0)
	s_barrier
	ds_read_b128 v[128:131], v128
	v_and_b32_e32 v134, 15, v136
	v_bitop3_b32 v133, v133, v134, 1 bitop3:0x36
	v_lshl_or_b32 v132, v133, 4, v132
	ds_read_b128 v[132:135], v132
	s_waitcnt lgkmcnt(0)
	v_cvt_f32_f16_e32 v137, v128
	v_cvt_f32_f16_e32 v138, v129
	v_cvt_f32_f16_e32 v139, v130
	v_cvt_f32_f16_e32 v141, v131
	v_cvt_u32_f32_e32 v137, v137
	v_cvt_u32_f32_e32 v138, v138
	v_cvt_u32_f32_sdwa v139, v139 dst_sel:WORD_1 dst_unused:UNUSED_PAD src0_sel:DWORD
	v_cvt_u32_f32_sdwa v141, v141 dst_sel:BYTE_3 dst_unused:UNUSED_PAD src0_sel:DWORD
	v_and_b32_e32 v131, 0xffff0000, v131
	v_and_b32_e32 v142, 0xffff0000, v129
	v_lshl_or_b32 v129, v138, 8, v137
	v_or3_b32 v138, v129, v139, v141
	v_or_b32_sdwa v129, v131, v130 dst_sel:DWORD dst_unused:UNUSED_PAD src0_sel:DWORD src1_sel:WORD_1
	v_cvt_f32_f16_e32 v130, v132
	v_cvt_f32_f16_e32 v131, v133
	v_cvt_f32_f16_e32 v137, v134
	v_cvt_f32_f16_e32 v139, v135
	v_cvt_u32_f32_e32 v130, v130
	v_cvt_u32_f32_e32 v131, v131
	v_cvt_u32_f32_sdwa v137, v137 dst_sel:WORD_1 dst_unused:UNUSED_PAD src0_sel:DWORD
	v_cvt_u32_f32_sdwa v139, v139 dst_sel:BYTE_3 dst_unused:UNUSED_PAD src0_sel:DWORD
	v_and_b32_e32 v133, 0xffff0000, v133
	v_lshl_or_b32 v130, v131, 8, v130
	v_and_b32_e32 v135, 0xffff0000, v135
	v_or3_b32 v139, v130, v137, v139
	v_ashrrev_i32_e32 v137, 31, v136
	v_or_b32_sdwa v130, v133, v132 dst_sel:DWORD dst_unused:UNUSED_PAD src0_sel:DWORD src1_sel:WORD_1
	v_lshlrev_b64 v[132:133], 10, v[136:137]
	v_or_b32_sdwa v131, v135, v134 dst_sel:DWORD dst_unused:UNUSED_PAD src0_sel:DWORD src1_sel:WORD_1
	v_lshl_add_u64 v[132:133], s[12:13], 0, v[132:133]
	v_lshlrev_b32_e32 v134, 3, v140
	v_mov_b32_e32 v135, v164
	v_lshl_add_u64 v[132:133], v[132:133], 0, v[134:135]
	global_store_dwordx2 v[132:133], v[138:139], off
	v_lshlrev_b32_e32 v132, 4, v140
	v_or_b32_sdwa v128, v142, v128 dst_sel:DWORD dst_unused:UNUSED_PAD src0_sel:DWORD src1_sel:WORD_1
	v_lshl_or_b32 v132, v136, 11, v132
	buffer_store_dwordx4 v[128:131], v132, s[8:11], 0 offen sc1
	s_nop 1
	v_add_u32_e32 v128, 0x200, v156
	v_cndmask_b32_e64 v128, v128, v200, s[4:5]
	v_and_b32_e32 v140, 7, v128
	v_ashrrev_i32_e32 v136, 3, v128
	v_lshlrev_b32_e32 v132, 1, v140
	v_bitop3_b32 v128, v132, v136, 15 bitop3:0x78
	v_lshl_add_u32 v197, v136, 8, v192
	v_lshlrev_b32_e32 v199, 4, v128
	v_or_b32_e32 v128, v197, v199
	ds_read_b128 v[128:131], v128
	v_and_b32_e32 v133, 15, v136
	v_bitop3_b32 v132, v132, v133, 1 bitop3:0x36
	v_lshlrev_b32_e32 v198, 4, v132
	v_or_b32_e32 v132, v197, v198
	ds_read_b128 v[132:135], v132
	s_waitcnt lgkmcnt(1)
	v_cvt_f32_f16_e32 v137, v128
	v_cvt_f32_f16_e32 v138, v129
	v_cvt_f32_f16_e32 v139, v130
	v_cvt_f32_f16_e32 v141, v131
	v_cvt_u32_f32_e32 v137, v137
	v_cvt_u32_f32_e32 v138, v138
	v_cvt_u32_f32_sdwa v139, v139 dst_sel:WORD_1 dst_unused:UNUSED_PAD src0_sel:DWORD
	v_cvt_u32_f32_sdwa v141, v141 dst_sel:BYTE_3 dst_unused:UNUSED_PAD src0_sel:DWORD
	v_and_b32_e32 v131, 0xffff0000, v131
	v_and_b32_e32 v142, 0xffff0000, v129
	v_lshl_or_b32 v129, v138, 8, v137
	v_or3_b32 v138, v129, v139, v141
	v_or_b32_sdwa v129, v131, v130 dst_sel:DWORD dst_unused:UNUSED_PAD src0_sel:DWORD src1_sel:WORD_1
	s_waitcnt lgkmcnt(0)
	v_cvt_f32_f16_e32 v130, v132
	v_cvt_f32_f16_e32 v131, v133
	v_cvt_f32_f16_e32 v137, v134
	v_cvt_f32_f16_e32 v139, v135
	v_cvt_u32_f32_e32 v130, v130
	v_cvt_u32_f32_e32 v131, v131
	v_cvt_u32_f32_sdwa v137, v137 dst_sel:WORD_1 dst_unused:UNUSED_PAD src0_sel:DWORD
	v_cvt_u32_f32_sdwa v139, v139 dst_sel:BYTE_3 dst_unused:UNUSED_PAD src0_sel:DWORD
	v_and_b32_e32 v133, 0xffff0000, v133
	v_lshl_or_b32 v130, v131, 8, v130
	v_and_b32_e32 v135, 0xffff0000, v135
	v_or3_b32 v139, v130, v137, v139
	v_ashrrev_i32_e32 v137, 31, v136
	v_or_b32_sdwa v130, v133, v132 dst_sel:DWORD dst_unused:UNUSED_PAD src0_sel:DWORD src1_sel:WORD_1
	v_lshlrev_b64 v[132:133], 10, v[136:137]
	v_or_b32_sdwa v131, v135, v134 dst_sel:DWORD dst_unused:UNUSED_PAD src0_sel:DWORD src1_sel:WORD_1
	v_lshl_add_u64 v[132:133], s[12:13], 0, v[132:133]
	v_lshlrev_b32_e32 v134, 3, v140
	v_mov_b32_e32 v135, v164
	v_lshl_add_u64 v[150:151], v[132:133], 0, v[134:135]
	v_lshlrev_b32_e32 v132, 4, v140
	v_or_b32_sdwa v128, v142, v128 dst_sel:DWORD dst_unused:UNUSED_PAD src0_sel:DWORD src1_sel:WORD_1
	v_lshl_or_b32 v196, v136, 11, v132
	global_store_dwordx2 v[150:151], v[138:139], off
	buffer_store_dwordx4 v[128:131], v196, s[8:11], 0 offen sc1
	v_add_u32_e32 v132, 0x600, v156
	v_ashrrev_i32_e32 v142, 3, v132
	v_add_u32_e32 v128, 0x300, v156
	v_and_b32_e32 v129, 7, v157
	v_add_u32_e32 v130, 0x400, v156
	v_add_u32_e32 v131, 0x500, v156
	v_ashrrev_i32_e32 v148, 3, v128
	v_lshlrev_b32_e32 v160, 1, v129
	v_lshlrev_b32_e32 v140, 3, v129
	v_lshlrev_b32_e32 v159, 4, v129
	v_ashrrev_i32_e32 v146, 3, v130
	v_ashrrev_i32_e32 v144, 3, v131
	s_and_saveexec_b64 s[4:5], vcc
	s_xor_b64 s[4:5], exec, s[4:5]
	s_cbranch_execz .LBB0_459
	v_lshl_add_u32 v129, v148, 8, v192
	v_bitop3_b32 v128, v148, v160, 15 bitop3:0x6c
	v_lshl_or_b32 v130, v128, 4, v129
	v_or_b32_e32 v128, 1, v160
	v_bitop3_b32 v131, v148, v128, 15 bitop3:0x6c
	v_lshl_or_b32 v129, v131, 4, v129
	ds_read_b128 v[130:133], v130
	v_ashrrev_i32_e32 v149, 31, v148
	v_mov_b32_e32 v141, v164
	v_ashrrev_i32_e32 v147, 31, v146
	v_ashrrev_i32_e32 v145, 31, v144
	s_waitcnt lgkmcnt(0)
	v_and_b32_e32 v135, 0xffff0000, v131
	v_cvt_f32_f16_e32 v136, v130
	v_cvt_f32_f16_e32 v131, v131
	v_and_b32_e32 v134, 0xffff0000, v133
	v_cvt_f32_f16_e32 v137, v132
	v_cvt_f32_f16_e32 v133, v133
	v_cvt_u32_f32_e32 v136, v136
	v_cvt_u32_f32_e32 v131, v131
	v_cvt_u32_f32_sdwa v137, v137 dst_sel:WORD_1 dst_unused:UNUSED_PAD src0_sel:DWORD
	v_cvt_u32_f32_sdwa v133, v133 dst_sel:BYTE_3 dst_unused:UNUSED_PAD src0_sel:DWORD
	v_or_b32_sdwa v130, v135, v130 dst_sel:DWORD dst_unused:UNUSED_PAD src0_sel:DWORD src1_sel:WORD_1
	v_lshl_or_b32 v131, v131, 8, v136
	v_ashrrev_i32_e32 v143, 31, v142
	v_or3_b32 v136, v131, v137, v133
	v_or_b32_sdwa v131, v134, v132 dst_sel:DWORD dst_unused:UNUSED_PAD src0_sel:DWORD src1_sel:WORD_1
	ds_read_b128 v[132:135], v129
	s_waitcnt lgkmcnt(0)
	v_and_b32_e32 v138, 0xffff0000, v133
	v_cvt_f32_f16_e32 v137, v132
	v_cvt_f32_f16_e32 v133, v133
	v_and_b32_e32 v129, 0xffff0000, v135
	v_cvt_f32_f16_e32 v139, v134
	v_cvt_f32_f16_e32 v135, v135
	v_cvt_u32_f32_e32 v137, v137
	v_cvt_u32_f32_e32 v133, v133
	v_cvt_u32_f32_sdwa v139, v139 dst_sel:WORD_1 dst_unused:UNUSED_PAD src0_sel:DWORD
	v_cvt_u32_f32_sdwa v135, v135 dst_sel:BYTE_3 dst_unused:UNUSED_PAD src0_sel:DWORD
	v_or_b32_sdwa v132, v138, v132 dst_sel:DWORD dst_unused:UNUSED_PAD src0_sel:DWORD src1_sel:WORD_1
	v_lshl_or_b32 v133, v133, 8, v137
	v_or3_b32 v137, v133, v139, v135
	v_or_b32_sdwa v133, v129, v134 dst_sel:DWORD dst_unused:UNUSED_PAD src0_sel:DWORD src1_sel:WORD_1
	v_lshlrev_b64 v[134:135], 10, v[148:149]
	v_lshl_add_u64 v[134:135], s[12:13], 0, v[134:135]
	v_lshl_add_u64 v[134:135], v[134:135], 0, v[140:141]
	v_lshl_or_b32 v129, v148, 11, v159
	global_store_dwordx2 v[134:135], v[136:137], off
	buffer_store_dwordx4 v[130:133], v129, s[8:11], 0 offen sc1
	v_lshl_add_u32 v129, v146, 8, v192
	s_nop 0
	v_bitop3_b32 v130, v146, v160, 15 bitop3:0x6c
	v_lshl_or_b32 v130, v130, 4, v129
	v_bitop3_b32 v131, v146, v128, 15 bitop3:0x6c
	v_lshl_or_b32 v129, v131, 4, v129
	ds_read_b128 v[130:133], v130
	s_waitcnt lgkmcnt(0)
	v_and_b32_e32 v135, 0xffff0000, v131
	v_cvt_f32_f16_e32 v136, v130
	v_cvt_f32_f16_e32 v131, v131
	v_and_b32_e32 v134, 0xffff0000, v133
	v_cvt_f32_f16_e32 v137, v132
	v_cvt_f32_f16_e32 v133, v133
	v_cvt_u32_f32_e32 v136, v136
	v_cvt_u32_f32_e32 v131, v131
	v_cvt_u32_f32_sdwa v137, v137 dst_sel:WORD_1 dst_unused:UNUSED_PAD src0_sel:DWORD
	v_cvt_u32_f32_sdwa v133, v133 dst_sel:BYTE_3 dst_unused:UNUSED_PAD src0_sel:DWORD
	v_or_b32_sdwa v130, v135, v130 dst_sel:DWORD dst_unused:UNUSED_PAD src0_sel:DWORD src1_sel:WORD_1
	v_lshl_or_b32 v131, v131, 8, v136
	v_or3_b32 v136, v131, v137, v133
	v_or_b32_sdwa v131, v134, v132 dst_sel:DWORD dst_unused:UNUSED_PAD src0_sel:DWORD src1_sel:WORD_1
	ds_read_b128 v[132:135], v129
	s_waitcnt lgkmcnt(0)
	v_and_b32_e32 v138, 0xffff0000, v133
	v_cvt_f32_f16_e32 v137, v132
	v_cvt_f32_f16_e32 v133, v133
	v_and_b32_e32 v129, 0xffff0000, v135
	v_cvt_f32_f16_e32 v139, v134
	v_cvt_f32_f16_e32 v135, v135
	v_cvt_u32_f32_e32 v137, v137
	v_cvt_u32_f32_e32 v133, v133
	v_cvt_u32_f32_sdwa v139, v139 dst_sel:WORD_1 dst_unused:UNUSED_PAD src0_sel:DWORD
	v_cvt_u32_f32_sdwa v135, v135 dst_sel:BYTE_3 dst_unused:UNUSED_PAD src0_sel:DWORD
	v_or_b32_sdwa v132, v138, v132 dst_sel:DWORD dst_unused:UNUSED_PAD src0_sel:DWORD src1_sel:WORD_1
	v_lshl_or_b32 v133, v133, 8, v137
	v_or3_b32 v137, v133, v139, v135
	v_or_b32_sdwa v133, v129, v134 dst_sel:DWORD dst_unused:UNUSED_PAD src0_sel:DWORD src1_sel:WORD_1
	v_lshlrev_b64 v[134:135], 10, v[146:147]
	v_lshl_add_u64 v[134:135], s[12:13], 0, v[134:135]
	v_lshl_add_u64 v[134:135], v[134:135], 0, v[140:141]
	v_lshl_or_b32 v129, v146, 11, v159
	global_store_dwordx2 v[134:135], v[136:137], off
	buffer_store_dwordx4 v[130:133], v129, s[8:11], 0 offen sc1
	v_lshl_add_u32 v129, v144, 8, v192
	s_nop 0
	v_bitop3_b32 v130, v144, v160, 15 bitop3:0x6c
	v_lshl_or_b32 v130, v130, 4, v129
	v_bitop3_b32 v131, v144, v128, 15 bitop3:0x6c
	v_lshl_or_b32 v129, v131, 4, v129
	ds_read_b128 v[130:133], v130
	v_bitop3_b32 v128, v142, v128, 15 bitop3:0x6c
	s_waitcnt lgkmcnt(0)
	v_and_b32_e32 v135, 0xffff0000, v131
	v_cvt_f32_f16_e32 v136, v130
	v_cvt_f32_f16_e32 v131, v131
	v_and_b32_e32 v134, 0xffff0000, v133
	v_cvt_f32_f16_e32 v137, v132
	v_cvt_f32_f16_e32 v133, v133
	v_cvt_u32_f32_e32 v136, v136
	v_cvt_u32_f32_e32 v131, v131
	v_cvt_u32_f32_sdwa v137, v137 dst_sel:WORD_1 dst_unused:UNUSED_PAD src0_sel:DWORD
	v_cvt_u32_f32_sdwa v133, v133 dst_sel:BYTE_3 dst_unused:UNUSED_PAD src0_sel:DWORD
	v_or_b32_sdwa v130, v135, v130 dst_sel:DWORD dst_unused:UNUSED_PAD src0_sel:DWORD src1_sel:WORD_1
	v_lshl_or_b32 v131, v131, 8, v136
	v_or3_b32 v136, v131, v137, v133
	v_or_b32_sdwa v131, v134, v132 dst_sel:DWORD dst_unused:UNUSED_PAD src0_sel:DWORD src1_sel:WORD_1
	ds_read_b128 v[132:135], v129
	s_waitcnt lgkmcnt(0)
	v_and_b32_e32 v138, 0xffff0000, v133
	v_cvt_f32_f16_e32 v137, v132
	v_cvt_f32_f16_e32 v133, v133
	v_and_b32_e32 v129, 0xffff0000, v135
	v_cvt_f32_f16_e32 v139, v134
	v_cvt_f32_f16_e32 v135, v135
	v_cvt_u32_f32_e32 v137, v137
	v_cvt_u32_f32_e32 v133, v133
	v_cvt_u32_f32_sdwa v139, v139 dst_sel:WORD_1 dst_unused:UNUSED_PAD src0_sel:DWORD
	v_cvt_u32_f32_sdwa v135, v135 dst_sel:BYTE_3 dst_unused:UNUSED_PAD src0_sel:DWORD
	v_or_b32_sdwa v132, v138, v132 dst_sel:DWORD dst_unused:UNUSED_PAD src0_sel:DWORD src1_sel:WORD_1
	v_lshl_or_b32 v133, v133, 8, v137
	v_or3_b32 v137, v133, v139, v135
	v_or_b32_sdwa v133, v129, v134 dst_sel:DWORD dst_unused:UNUSED_PAD src0_sel:DWORD src1_sel:WORD_1
	v_lshlrev_b64 v[134:135], 10, v[144:145]
	v_lshl_add_u64 v[134:135], s[12:13], 0, v[134:135]
	v_lshl_add_u64 v[134:135], v[134:135], 0, v[140:141]
	v_lshl_or_b32 v129, v144, 11, v159
	global_store_dwordx2 v[134:135], v[136:137], off
	buffer_store_dwordx4 v[130:133], v129, s[8:11], 0 offen sc1
	v_lshl_add_u32 v129, v142, 8, v192
	s_nop 0
	v_bitop3_b32 v130, v142, v160, 15 bitop3:0x6c
	v_lshl_or_b32 v130, v130, 4, v129
	v_lshl_or_b32 v132, v128, 4, v129
	ds_read_b128 v[128:131], v130
	s_waitcnt lgkmcnt(0)
	v_and_b32_e32 v135, 0xffff0000, v129
	v_cvt_f32_f16_e32 v134, v128
	v_cvt_f32_f16_e32 v129, v129
	v_and_b32_e32 v133, 0xffff0000, v131
	v_cvt_f32_f16_e32 v136, v130
	v_cvt_f32_f16_e32 v131, v131
	v_cvt_u32_f32_e32 v134, v134
	v_cvt_u32_f32_e32 v129, v129
	v_cvt_u32_f32_sdwa v136, v136 dst_sel:WORD_1 dst_unused:UNUSED_PAD src0_sel:DWORD
	v_cvt_u32_f32_sdwa v131, v131 dst_sel:BYTE_3 dst_unused:UNUSED_PAD src0_sel:DWORD
	v_or_b32_sdwa v128, v135, v128 dst_sel:DWORD dst_unused:UNUSED_PAD src0_sel:DWORD src1_sel:WORD_1
	v_lshl_or_b32 v129, v129, 8, v134
	v_or3_b32 v134, v129, v136, v131
	v_or_b32_sdwa v129, v133, v130 dst_sel:DWORD dst_unused:UNUSED_PAD src0_sel:DWORD src1_sel:WORD_1
	ds_read_b128 v[130:133], v132
	s_waitcnt lgkmcnt(0)
	v_and_b32_e32 v137, 0xffff0000, v131
	v_cvt_f32_f16_e32 v135, v130
	v_cvt_f32_f16_e32 v131, v131
	v_and_b32_e32 v136, 0xffff0000, v133
	v_cvt_f32_f16_e32 v138, v132
	v_cvt_f32_f16_e32 v133, v133
	v_cvt_u32_f32_e32 v135, v135
	v_cvt_u32_f32_e32 v131, v131
	v_cvt_u32_f32_sdwa v138, v138 dst_sel:WORD_1 dst_unused:UNUSED_PAD src0_sel:DWORD
	v_cvt_u32_f32_sdwa v133, v133 dst_sel:BYTE_3 dst_unused:UNUSED_PAD src0_sel:DWORD
	v_or_b32_sdwa v130, v137, v130 dst_sel:DWORD dst_unused:UNUSED_PAD src0_sel:DWORD src1_sel:WORD_1
	v_lshl_or_b32 v131, v131, 8, v135
	v_or3_b32 v135, v131, v138, v133
	v_or_b32_sdwa v131, v136, v132 dst_sel:DWORD dst_unused:UNUSED_PAD src0_sel:DWORD src1_sel:WORD_1
	v_lshlrev_b64 v[132:133], 10, v[142:143]
	v_lshl_add_u64 v[132:133], s[12:13], 0, v[132:133]
	v_lshl_add_u64 v[132:133], v[132:133], 0, v[140:141]
	global_store_dwordx2 v[132:133], v[134:135], off
	v_lshl_or_b32 v132, v142, 11, v159
	buffer_store_dwordx4 v[128:131], v132, s[8:11], 0 offen sc1

.LBB0_463:
	s_mov_b32 s100, 0xbfb8aa3b
	s_mov_b32 s101, 0x437f0000
	s_or_b64 exec, exec, s[16:17]
	s_waitcnt lgkmcnt(0)
	s_barrier
	global_load_dwordx4 v[132:135], v[152:153], off offset:256
	global_load_dwordx4 v[128:131], v[154:155], off offset:256
	v_lshlrev_b32_e32 v152, 16, v180
	v_and_b32_e32 v153, 0xffff0000, v180
	v_lshlrev_b32_e32 v154, 16, v181
	v_and_b32_e32 v155, 0xffff0000, v181
	s_waitcnt vmcnt(1)
	v_add_f32_e32 v147, v116, v132
	v_med3_f32 v147, v147, s6, v191
	s_waitcnt vmcnt(0)
	v_add_f32_e32 v149, v112, v128
	v_med3_f32 v149, v149, s6, v191
	v_mul_f32_e32 v147, s100, v147
	v_exp_f32_e32 v156, v147
	v_mul_f32_e32 v147, s100, v149
	v_add_f32_e32 v149, v117, v133
	v_med3_f32 v149, v149, s6, v191
	v_add_f32_e32 v157, v113, v129
	v_med3_f32 v180, v157, s6, v191
	v_mul_f32_e32 v149, s100, v149
	v_exp_f32_e32 v157, v149
	v_mul_f32_e32 v149, s100, v180
	v_exp_f32_e32 v147, v147
	v_exp_f32_e32 v149, v149
	v_pk_add_f32 v[156:157], v[156:157], 1.0 op_sel_hi:[1,0]
	v_add_f32_e32 v147, 1.0, v147
	v_add_f32_e32 v149, 1.0, v149
	v_mul_f32_e32 v180, v156, v147
	v_mul_f32_e32 v181, v157, v149
	v_rcp_f32_e32 v180, v180
	v_rcp_f32_e32 v181, v181
	v_mul_f32_e32 v147, v147, v180
	v_pk_mul_f32 v[156:157], v[156:157], v[180:181]
	v_mul_f32_e32 v149, v149, v181
	v_pk_mul_f32 v[152:153], v[156:157], v[152:153]
	v_add_f32_e32 v156, v115, v131
	v_cvt_pk_f16_f32 v180, v152, v153
	v_add_f32_e32 v153, v114, v130
	v_med3_f32 v153, v153, s6, v191
	v_mul_f32_e32 v153, s100, v153
	v_exp_f32_e32 v153, v153
	v_add_f32_e32 v152, v118, v134
	v_med3_f32 v152, v152, s6, v191
	v_mul_f32_e32 v152, s100, v152
	v_add_f32_e32 v157, 1.0, v153
	v_add_f32_e32 v153, v119, v135
	v_med3_f32 v153, v153, s6, v191
	v_med3_f32 v156, v156, s6, v191
	v_mul_f32_e32 v153, s100, v153
	v_exp_f32_e32 v152, v152
	v_exp_f32_e32 v153, v153
	v_mul_f32_e32 v156, s100, v156
	v_exp_f32_e32 v156, v156
	v_mul_f32_e32 v147, s101, v147
	v_pk_add_f32 v[152:153], v[152:153], 1.0 op_sel_hi:[1,0]
	v_rndne_f32_e32 v147, v147
	v_add_f32_e32 v181, 1.0, v156
	v_mul_f32_e32 v156, v152, v157
	v_rcp_f32_e32 v156, v156
	v_mul_f32_e32 v149, s101, v149
	v_rndne_f32_e32 v149, v149
	v_mul_f32_e32 v157, v157, v156
	v_mul_f32_e32 v157, s101, v157
	v_rndne_f32_e32 v157, v157
	v_cvt_f16_f32_e32 v201, v157
	v_mul_f32_e32 v157, v153, v181
	v_rcp_f32_e32 v157, v157
	v_cvt_f16_f32_e32 v147, v147
	v_cvt_f16_f32_e32 v149, v149
	v_pk_mul_f32 v[152:153], v[152:153], v[156:157]
	s_nop 0
	v_pk_mul_f32 v[152:153], v[152:153], v[154:155]
	s_nop 0
	v_cvt_pk_f16_f32 v152, v152, v153
	v_mul_f32_e32 v153, v181, v157
	v_mul_f32_e32 v153, s101, v153
	v_rndne_f32_e32 v153, v153
	v_cvt_f16_f32_e32 v153, v153
	v_pack_b32_f16 v154, v201, v152
	v_add_f32_e32 v157, v97, v129
	v_bfi_b32 v155, s98, v153, v152
	v_pack_b32_f16 v152, v147, v180
	v_add_f32_e32 v147, v100, v132
	v_bfi_b32 v153, s98, v149, v180
	v_med3_f32 v147, v147, s6, v191
	v_add_f32_e32 v149, v96, v128
	v_med3_f32 v149, v149, s6, v191
	v_mul_f32_e32 v147, s100, v147
	v_exp_f32_e32 v156, v147
	v_mul_f32_e32 v147, s100, v149
	v_add_f32_e32 v149, v101, v133
	v_med3_f32 v149, v149, s6, v191
	ds_write_b128 v158, v[152:155]
	v_lshlrev_b32_e32 v154, 16, v178
	v_and_b32_e32 v155, 0xffff0000, v178
	v_med3_f32 v178, v157, s6, v191
	v_mul_f32_e32 v149, s100, v149
	v_exp_f32_e32 v157, v149
	v_mul_f32_e32 v149, s100, v178
	v_exp_f32_e32 v147, v147
	v_exp_f32_e32 v149, v149
	v_pk_add_f32 v[156:157], v[156:157], 1.0 op_sel_hi:[1,0]
	v_lshlrev_b32_e32 v152, 16, v179
	v_add_f32_e32 v147, 1.0, v147
	v_add_f32_e32 v149, 1.0, v149
	v_and_b32_e32 v153, 0xffff0000, v179
	v_mul_f32_e32 v178, v156, v147
	v_mul_f32_e32 v179, v157, v149
	v_rcp_f32_e32 v178, v178
	v_rcp_f32_e32 v179, v179
	v_mul_f32_e32 v147, v147, v178
	v_pk_mul_f32 v[156:157], v[156:157], v[178:179]
	v_mul_f32_e32 v149, v149, v179
	v_pk_mul_f32 v[154:155], v[156:157], v[154:155]
	v_add_f32_e32 v156, v99, v131
	v_cvt_pk_f16_f32 v178, v154, v155
	v_add_f32_e32 v155, v98, v130
	v_med3_f32 v155, v155, s6, v191
	v_mul_f32_e32 v155, s100, v155
	v_exp_f32_e32 v155, v155
	v_add_f32_e32 v154, v102, v134
	v_med3_f32 v154, v154, s6, v191
	v_mul_f32_e32 v154, s100, v154
	v_add_f32_e32 v157, 1.0, v155
	v_add_f32_e32 v155, v103, v135
	v_med3_f32 v155, v155, s6, v191
	v_med3_f32 v156, v156, s6, v191
	v_mul_f32_e32 v155, s100, v155
	v_exp_f32_e32 v154, v154
	v_exp_f32_e32 v155, v155
	v_mul_f32_e32 v156, s100, v156
	v_exp_f32_e32 v156, v156
	v_mul_f32_e32 v147, s101, v147
	v_pk_add_f32 v[154:155], v[154:155], 1.0 op_sel_hi:[1,0]
	v_rndne_f32_e32 v147, v147
	v_add_f32_e32 v179, 1.0, v156
	v_mul_f32_e32 v156, v154, v157
	v_rcp_f32_e32 v156, v156
	v_mul_f32_e32 v149, s101, v149
	v_rndne_f32_e32 v149, v149
	v_mul_f32_e32 v157, v157, v156
	v_mul_f32_e32 v157, s101, v157
	v_rndne_f32_e32 v157, v157
	v_cvt_f16_f32_e32 v180, v157
	v_mul_f32_e32 v157, v155, v179
	v_rcp_f32_e32 v157, v157
	v_cvt_f16_f32_e32 v147, v147
	v_cvt_f16_f32_e32 v149, v149
	v_pk_mul_f32 v[154:155], v[154:155], v[156:157]
	s_nop 0
	v_pk_mul_f32 v[152:153], v[154:155], v[152:153]
	s_nop 0
	v_cvt_pk_f16_f32 v152, v152, v153
	v_mul_f32_e32 v153, v179, v157
	v_mul_f32_e32 v153, s101, v153
	v_rndne_f32_e32 v153, v153
	v_cvt_f16_f32_e32 v153, v153
	v_pack_b32_f16 v154, v180, v152
	v_add_f32_e32 v157, v81, v129
	v_bfi_b32 v155, s98, v153, v152
	v_pack_b32_f16 v152, v147, v178
	v_add_f32_e32 v147, v84, v132
	v_bfi_b32 v153, s98, v149, v178
	v_med3_f32 v147, v147, s6, v191
	v_add_f32_e32 v149, v80, v128
	v_med3_f32 v149, v149, s6, v191
	v_mul_f32_e32 v147, s100, v147
	v_exp_f32_e32 v156, v147
	v_mul_f32_e32 v147, s100, v149
	v_add_f32_e32 v149, v85, v133
	v_med3_f32 v149, v149, s6, v191
	ds_write_b128 v158, v[152:155] offset:4096
	v_lshlrev_b32_e32 v152, 16, v176
	v_and_b32_e32 v153, 0xffff0000, v176
	v_med3_f32 v176, v157, s6, v191
	v_mul_f32_e32 v149, s100, v149
	v_exp_f32_e32 v157, v149
	v_mul_f32_e32 v149, s100, v176
	v_exp_f32_e32 v147, v147
	v_exp_f32_e32 v149, v149
	v_pk_add_f32 v[156:157], v[156:157], 1.0 op_sel_hi:[1,0]
	v_lshlrev_b32_e32 v154, 16, v177
	v_add_f32_e32 v147, 1.0, v147
	v_add_f32_e32 v149, 1.0, v149
	v_and_b32_e32 v155, 0xffff0000, v177
	v_mul_f32_e32 v176, v156, v147
	v_mul_f32_e32 v177, v157, v149
	v_rcp_f32_e32 v176, v176
	v_rcp_f32_e32 v177, v177
	v_mul_f32_e32 v147, v147, v176
	v_pk_mul_f32 v[156:157], v[156:157], v[176:177]
	v_mul_f32_e32 v149, v149, v177
	v_pk_mul_f32 v[152:153], v[156:157], v[152:153]
	v_add_f32_e32 v156, v83, v131
	v_cvt_pk_f16_f32 v176, v152, v153
	v_add_f32_e32 v153, v82, v130
	v_med3_f32 v153, v153, s6, v191
	v_mul_f32_e32 v153, s100, v153
	v_exp_f32_e32 v153, v153
	v_add_f32_e32 v152, v86, v134
	v_med3_f32 v152, v152, s6, v191
	v_mul_f32_e32 v152, s100, v152
	v_add_f32_e32 v157, 1.0, v153
	v_add_f32_e32 v153, v87, v135
	v_med3_f32 v153, v153, s6, v191
	v_med3_f32 v156, v156, s6, v191
	v_mul_f32_e32 v153, s100, v153
	v_exp_f32_e32 v152, v152
	v_exp_f32_e32 v153, v153
	v_mul_f32_e32 v156, s100, v156
	v_exp_f32_e32 v156, v156
	v_mul_f32_e32 v147, s101, v147
	v_pk_add_f32 v[152:153], v[152:153], 1.0 op_sel_hi:[1,0]
	v_rndne_f32_e32 v147, v147
	v_add_f32_e32 v177, 1.0, v156
	v_mul_f32_e32 v156, v152, v157
	v_rcp_f32_e32 v156, v156
	v_mul_f32_e32 v149, s101, v149
	v_rndne_f32_e32 v149, v149
	v_mul_f32_e32 v157, v157, v156
	v_mul_f32_e32 v157, s101, v157
	v_rndne_f32_e32 v157, v157
	v_cvt_f16_f32_e32 v178, v157
	v_mul_f32_e32 v157, v153, v177
	v_rcp_f32_e32 v157, v157
	v_cvt_f16_f32_e32 v147, v147
	v_cvt_f16_f32_e32 v149, v149
	v_pk_mul_f32 v[152:153], v[152:153], v[156:157]
	s_nop 0
	v_pk_mul_f32 v[152:153], v[152:153], v[154:155]
	s_nop 0
	v_cvt_pk_f16_f32 v152, v152, v153
	v_mul_f32_e32 v153, v177, v157
	v_mul_f32_e32 v153, s101, v153
	v_rndne_f32_e32 v153, v153
	v_cvt_f16_f32_e32 v153, v153
	v_pack_b32_f16 v154, v178, v152
	v_add_f32_e32 v157, v65, v129
	v_bfi_b32 v155, s98, v153, v152
	v_pack_b32_f16 v152, v147, v176
	v_add_f32_e32 v147, v68, v132
	v_bfi_b32 v153, s98, v149, v176
	v_med3_f32 v147, v147, s6, v191
	v_add_f32_e32 v149, v64, v128
	v_med3_f32 v149, v149, s6, v191
	v_mul_f32_e32 v147, s100, v147
	v_exp_f32_e32 v156, v147
	v_mul_f32_e32 v147, s100, v149
	v_add_f32_e32 v149, v69, v133
	v_med3_f32 v149, v149, s6, v191
	ds_write_b128 v158, v[152:155] offset:8192
	v_lshlrev_b32_e32 v152, 16, v174
	v_and_b32_e32 v153, 0xffff0000, v174
	v_med3_f32 v174, v157, s6, v191
	v_mul_f32_e32 v149, s100, v149
	v_exp_f32_e32 v157, v149
	v_mul_f32_e32 v149, s100, v174
	v_exp_f32_e32 v147, v147
	v_exp_f32_e32 v149, v149
	v_pk_add_f32 v[156:157], v[156:157], 1.0 op_sel_hi:[1,0]
	v_lshlrev_b32_e32 v154, 16, v175
	v_add_f32_e32 v147, 1.0, v147
	v_add_f32_e32 v149, 1.0, v149
	v_and_b32_e32 v155, 0xffff0000, v175
	v_mul_f32_e32 v174, v156, v147
	v_mul_f32_e32 v175, v157, v149
	v_rcp_f32_e32 v174, v174
	v_rcp_f32_e32 v175, v175
	v_mul_f32_e32 v147, v147, v174
	v_pk_mul_f32 v[156:157], v[156:157], v[174:175]
	v_mul_f32_e32 v149, v149, v175
	v_pk_mul_f32 v[152:153], v[156:157], v[152:153]
	v_add_f32_e32 v156, v67, v131
	v_cvt_pk_f16_f32 v174, v152, v153
	v_add_f32_e32 v153, v66, v130
	v_med3_f32 v153, v153, s6, v191
	v_mul_f32_e32 v153, s100, v153
	v_exp_f32_e32 v153, v153
	v_add_f32_e32 v152, v70, v134
	v_med3_f32 v152, v152, s6, v191
	v_mul_f32_e32 v152, s100, v152
	v_add_f32_e32 v157, 1.0, v153
	v_add_f32_e32 v153, v71, v135
	v_med3_f32 v153, v153, s6, v191
	v_med3_f32 v156, v156, s6, v191
	v_mul_f32_e32 v153, s100, v153
	v_exp_f32_e32 v152, v152
	v_exp_f32_e32 v153, v153
	v_mul_f32_e32 v156, s100, v156
	v_exp_f32_e32 v156, v156
	v_mul_f32_e32 v147, s101, v147
	v_pk_add_f32 v[152:153], v[152:153], 1.0 op_sel_hi:[1,0]
	v_rndne_f32_e32 v147, v147
	v_add_f32_e32 v175, 1.0, v156
	v_mul_f32_e32 v156, v152, v157
	v_rcp_f32_e32 v156, v156
	v_mul_f32_e32 v149, s101, v149
	v_rndne_f32_e32 v149, v149
	v_mul_f32_e32 v157, v157, v156
	v_mul_f32_e32 v157, s101, v157
	v_rndne_f32_e32 v157, v157
	v_cvt_f16_f32_e32 v176, v157
	v_mul_f32_e32 v157, v153, v175
	v_rcp_f32_e32 v157, v157
	v_cvt_f16_f32_e32 v147, v147
	v_cvt_f16_f32_e32 v149, v149
	v_pk_mul_f32 v[152:153], v[152:153], v[156:157]
	s_nop 0
	v_pk_mul_f32 v[152:153], v[152:153], v[154:155]
	s_nop 0
	v_cvt_pk_f16_f32 v152, v152, v153
	v_mul_f32_e32 v153, v175, v157
	v_mul_f32_e32 v153, s101, v153
	v_rndne_f32_e32 v153, v153
	v_cvt_f16_f32_e32 v153, v153
	v_pack_b32_f16 v154, v176, v152
	v_add_f32_e32 v157, v49, v129
	v_bfi_b32 v155, s98, v153, v152
	v_pack_b32_f16 v152, v147, v174
	v_add_f32_e32 v147, v52, v132
	v_bfi_b32 v153, s98, v149, v174
	v_med3_f32 v147, v147, s6, v191
	v_add_f32_e32 v149, v48, v128
	v_med3_f32 v149, v149, s6, v191
	v_mul_f32_e32 v147, s100, v147
	v_exp_f32_e32 v156, v147
	v_mul_f32_e32 v147, s100, v149
	v_add_f32_e32 v149, v53, v133
	v_med3_f32 v149, v149, s6, v191
	ds_write_b128 v158, v[152:155] offset:12288
	v_lshlrev_b32_e32 v152, 16, v172
	v_and_b32_e32 v153, 0xffff0000, v172
	v_med3_f32 v172, v157, s6, v191
	v_mul_f32_e32 v149, s100, v149
	v_exp_f32_e32 v157, v149
	v_mul_f32_e32 v149, s100, v172
	v_exp_f32_e32 v147, v147
	v_exp_f32_e32 v149, v149
	v_pk_add_f32 v[156:157], v[156:157], 1.0 op_sel_hi:[1,0]
	v_lshlrev_b32_e32 v154, 16, v173
	v_add_f32_e32 v147, 1.0, v147
	v_add_f32_e32 v149, 1.0, v149
	v_and_b32_e32 v155, 0xffff0000, v173
	v_mul_f32_e32 v172, v156, v147
	v_mul_f32_e32 v173, v157, v149
	v_rcp_f32_e32 v172, v172
	v_rcp_f32_e32 v173, v173
	v_mul_f32_e32 v147, v147, v172
	v_pk_mul_f32 v[156:157], v[156:157], v[172:173]
	v_mul_f32_e32 v149, v149, v173
	v_pk_mul_f32 v[152:153], v[156:157], v[152:153]
	v_add_f32_e32 v156, v51, v131
	v_cvt_pk_f16_f32 v172, v152, v153
	v_add_f32_e32 v153, v50, v130
	v_med3_f32 v153, v153, s6, v191
	v_mul_f32_e32 v153, s100, v153
	v_exp_f32_e32 v153, v153
	v_add_f32_e32 v152, v54, v134
	v_med3_f32 v152, v152, s6, v191
	v_mul_f32_e32 v152, s100, v152
	v_add_f32_e32 v157, 1.0, v153
	v_add_f32_e32 v153, v55, v135
	v_med3_f32 v153, v153, s6, v191
	v_med3_f32 v156, v156, s6, v191
	v_mul_f32_e32 v153, s100, v153
	v_exp_f32_e32 v152, v152
	v_exp_f32_e32 v153, v153
	v_mul_f32_e32 v156, s100, v156
	v_exp_f32_e32 v156, v156
	v_mul_f32_e32 v147, s101, v147
	v_pk_add_f32 v[152:153], v[152:153], 1.0 op_sel_hi:[1,0]
	v_rndne_f32_e32 v147, v147
	v_add_f32_e32 v173, 1.0, v156
	v_mul_f32_e32 v156, v152, v157
	v_rcp_f32_e32 v156, v156
	v_mul_f32_e32 v149, s101, v149
	v_rndne_f32_e32 v149, v149
	v_mul_f32_e32 v157, v157, v156
	v_mul_f32_e32 v157, s101, v157
	v_rndne_f32_e32 v157, v157
	v_cvt_f16_f32_e32 v174, v157
	v_mul_f32_e32 v157, v153, v173
	v_rcp_f32_e32 v157, v157
	v_cvt_f16_f32_e32 v147, v147
	v_cvt_f16_f32_e32 v149, v149
	v_pk_mul_f32 v[152:153], v[152:153], v[156:157]
	s_nop 0
	v_pk_mul_f32 v[152:153], v[152:153], v[154:155]
	s_nop 0
	v_cvt_pk_f16_f32 v152, v152, v153
	v_mul_f32_e32 v153, v173, v157
	v_mul_f32_e32 v153, s101, v153
	v_rndne_f32_e32 v153, v153
	v_cvt_f16_f32_e32 v153, v153
	v_pack_b32_f16 v154, v174, v152
	v_add_f32_e32 v157, v33, v129
	v_bfi_b32 v155, s98, v153, v152
	v_pack_b32_f16 v152, v147, v172
	v_add_f32_e32 v147, v36, v132
	v_bfi_b32 v153, s98, v149, v172
	v_med3_f32 v147, v147, s6, v191
	v_add_f32_e32 v149, v32, v128
	v_med3_f32 v149, v149, s6, v191
	v_mul_f32_e32 v147, s100, v147
	v_exp_f32_e32 v156, v147
	v_mul_f32_e32 v147, s100, v149
	v_add_f32_e32 v149, v37, v133
	v_med3_f32 v149, v149, s6, v191
	ds_write_b128 v158, v[152:155] offset:16384
	v_lshlrev_b32_e32 v152, 16, v170
	v_and_b32_e32 v153, 0xffff0000, v170
	v_med3_f32 v170, v157, s6, v191
	v_mul_f32_e32 v149, s100, v149
	v_exp_f32_e32 v157, v149
	v_mul_f32_e32 v149, s100, v170
	v_exp_f32_e32 v147, v147
	v_exp_f32_e32 v149, v149
	v_pk_add_f32 v[156:157], v[156:157], 1.0 op_sel_hi:[1,0]
	v_lshlrev_b32_e32 v154, 16, v171
	v_add_f32_e32 v147, 1.0, v147
	v_add_f32_e32 v149, 1.0, v149
	v_and_b32_e32 v155, 0xffff0000, v171
	v_mul_f32_e32 v170, v156, v147
	v_mul_f32_e32 v171, v157, v149
	v_rcp_f32_e32 v170, v170
	v_rcp_f32_e32 v171, v171
	v_mul_f32_e32 v147, v147, v170
	v_pk_mul_f32 v[156:157], v[156:157], v[170:171]
	v_mul_f32_e32 v149, v149, v171
	v_pk_mul_f32 v[152:153], v[156:157], v[152:153]
	v_add_f32_e32 v156, v35, v131
	v_cvt_pk_f16_f32 v170, v152, v153
	v_add_f32_e32 v153, v34, v130
	v_med3_f32 v153, v153, s6, v191
	v_mul_f32_e32 v153, s100, v153
	v_exp_f32_e32 v153, v153
	v_add_f32_e32 v152, v38, v134
	v_med3_f32 v152, v152, s6, v191
	v_mul_f32_e32 v152, s100, v152
	v_add_f32_e32 v157, 1.0, v153
	v_add_f32_e32 v153, v39, v135
	v_med3_f32 v153, v153, s6, v191
	v_med3_f32 v156, v156, s6, v191
	v_mul_f32_e32 v153, s100, v153
	v_exp_f32_e32 v152, v152
	v_exp_f32_e32 v153, v153
	v_mul_f32_e32 v156, s100, v156
	v_exp_f32_e32 v156, v156
	v_mul_f32_e32 v147, s101, v147
	v_pk_add_f32 v[152:153], v[152:153], 1.0 op_sel_hi:[1,0]
	v_rndne_f32_e32 v147, v147
	v_add_f32_e32 v171, 1.0, v156
	v_mul_f32_e32 v156, v152, v157
	v_rcp_f32_e32 v156, v156
	v_mul_f32_e32 v149, s101, v149
	v_rndne_f32_e32 v149, v149
	v_mul_f32_e32 v157, v157, v156
	v_mul_f32_e32 v157, s101, v157
	v_rndne_f32_e32 v157, v157
	v_cvt_f16_f32_e32 v172, v157
	v_mul_f32_e32 v157, v153, v171
	v_rcp_f32_e32 v157, v157
	v_cvt_f16_f32_e32 v147, v147
	v_cvt_f16_f32_e32 v149, v149
	v_pk_mul_f32 v[152:153], v[152:153], v[156:157]
	s_nop 0
	v_pk_mul_f32 v[152:153], v[152:153], v[154:155]
	s_nop 0
	v_cvt_pk_f16_f32 v152, v152, v153
	v_mul_f32_e32 v153, v171, v157
	v_mul_f32_e32 v153, s101, v153
	v_rndne_f32_e32 v153, v153
	v_cvt_f16_f32_e32 v153, v153
	v_pack_b32_f16 v154, v172, v152
	v_add_f32_e32 v157, v17, v129
	v_add_f32_e32 v129, v1, v129
	v_bfi_b32 v155, s98, v153, v152
	v_pack_b32_f16 v152, v147, v170
	v_add_f32_e32 v147, v20, v132
	v_bfi_b32 v153, s98, v149, v170
	v_med3_f32 v147, v147, s6, v191
	v_add_f32_e32 v149, v16, v128
	v_med3_f32 v149, v149, s6, v191
	v_mul_f32_e32 v147, s100, v147
	v_exp_f32_e32 v156, v147
	v_mul_f32_e32 v147, s100, v149
	v_add_f32_e32 v149, v21, v133
	v_med3_f32 v149, v149, s6, v191
	ds_write_b128 v158, v[152:155] offset:20480
	v_lshlrev_b32_e32 v152, 16, v168
	v_and_b32_e32 v153, 0xffff0000, v168
	v_med3_f32 v168, v157, s6, v191
	v_mul_f32_e32 v149, s100, v149
	v_exp_f32_e32 v157, v149
	v_mul_f32_e32 v149, s100, v168
	v_exp_f32_e32 v147, v147
	v_exp_f32_e32 v149, v149
	v_pk_add_f32 v[156:157], v[156:157], 1.0 op_sel_hi:[1,0]
	v_lshlrev_b32_e32 v154, 16, v169
	v_add_f32_e32 v147, 1.0, v147
	v_add_f32_e32 v149, 1.0, v149
	v_and_b32_e32 v155, 0xffff0000, v169
	v_mul_f32_e32 v168, v156, v147
	v_mul_f32_e32 v169, v157, v149
	v_rcp_f32_e32 v168, v168
	v_rcp_f32_e32 v169, v169
	v_add_f32_e32 v132, v4, v132
	v_add_f32_e32 v128, v0, v128
	v_mul_f32_e32 v147, v147, v168
	v_pk_mul_f32 v[156:157], v[156:157], v[168:169]
	v_mul_f32_e32 v149, v149, v169
	v_pk_mul_f32 v[152:153], v[156:157], v[152:153]
	v_add_f32_e32 v156, v19, v131
	v_cvt_pk_f16_f32 v168, v152, v153
	v_add_f32_e32 v153, v18, v130
	v_med3_f32 v153, v153, s6, v191
	v_mul_f32_e32 v153, s100, v153
	v_exp_f32_e32 v153, v153
	v_add_f32_e32 v152, v22, v134
	v_med3_f32 v152, v152, s6, v191
	v_mul_f32_e32 v152, s100, v152
	v_add_f32_e32 v157, 1.0, v153
	v_add_f32_e32 v153, v23, v135
	v_med3_f32 v153, v153, s6, v191
	v_med3_f32 v156, v156, s6, v191
	v_mul_f32_e32 v153, s100, v153
	v_exp_f32_e32 v152, v152
	v_exp_f32_e32 v153, v153
	v_mul_f32_e32 v156, s100, v156
	v_exp_f32_e32 v156, v156
	v_mul_f32_e32 v147, s101, v147
	v_pk_add_f32 v[152:153], v[152:153], 1.0 op_sel_hi:[1,0]
	v_rndne_f32_e32 v147, v147
	v_add_f32_e32 v169, 1.0, v156
	v_mul_f32_e32 v156, v152, v157
	v_rcp_f32_e32 v156, v156
	v_cvt_f16_f32_e32 v147, v147
	v_med3_f32 v132, v132, s6, v191
	v_mul_f32_e32 v157, v157, v156
	v_mul_f32_e32 v157, s101, v157
	v_rndne_f32_e32 v157, v157
	v_cvt_f16_f32_e32 v170, v157
	v_mul_f32_e32 v157, v153, v169
	v_rcp_f32_e32 v157, v157
	v_mul_f32_e32 v149, s101, v149
	v_rndne_f32_e32 v149, v149
	v_pk_mul_f32 v[152:153], v[152:153], v[156:157]
	v_cvt_f16_f32_e32 v149, v149
	v_pk_mul_f32 v[152:153], v[152:153], v[154:155]
	s_nop 0
	v_cvt_pk_f16_f32 v152, v152, v153
	v_mul_f32_e32 v153, v169, v157
	v_mul_f32_e32 v153, s101, v153
	v_rndne_f32_e32 v153, v153
	v_cvt_f16_f32_e32 v153, v153
	v_pack_b32_f16 v154, v170, v152
	v_bfi_b32 v155, s98, v153, v152
	v_pack_b32_f16 v152, v147, v168
	v_med3_f32 v147, v128, s6, v191
	v_mul_f32_e32 v128, s100, v132
	v_mul_f32_e32 v132, s100, v147
	v_exp_f32_e32 v132, v132
	v_exp_f32_e32 v128, v128
	v_bfi_b32 v153, s98, v149, v168
	ds_write_b128 v158, v[152:155] offset:24576
	v_add_f32_e32 v147, 1.0, v132
	v_add_f32_e32 v132, v5, v133
	v_med3_f32 v132, v132, s6, v191
	v_med3_f32 v133, v129, s6, v191
	v_mul_f32_e32 v129, s100, v132
	v_exp_f32_e32 v129, v129
	v_mul_f32_e32 v132, s100, v133
	v_exp_f32_e32 v132, v132
	v_lshlrev_b32_e32 v152, 16, v166
	v_pk_add_f32 v[128:129], v[128:129], 1.0 op_sel_hi:[1,0]
	v_and_b32_e32 v153, 0xffff0000, v166
	v_add_f32_e32 v149, 1.0, v132
	v_mul_f32_e32 v132, v128, v147
	v_rcp_f32_e32 v132, v132
	v_lshlrev_b32_e32 v154, 16, v167
	v_and_b32_e32 v155, 0xffff0000, v167
	v_mul_f32_e32 v133, v147, v132
	v_mul_f32_e32 v133, s101, v133
	v_rndne_f32_e32 v133, v133
	v_cvt_f16_f32_e32 v147, v133
	v_mul_f32_e32 v133, v129, v149
	v_rcp_f32_e32 v133, v133
	s_nop 0
	v_pk_mul_f32 v[128:129], v[128:129], v[132:133]
	s_nop 0
	v_pk_mul_f32 v[128:129], v[128:129], v[152:153]
	s_nop 0
	v_cvt_pk_f16_f32 v132, v128, v129
	v_add_f32_e32 v129, v2, v130
	v_med3_f32 v129, v129, s6, v191
	v_mul_f32_e32 v129, s100, v129
	v_mul_f32_e32 v128, v149, v133
	v_exp_f32_e32 v129, v129
	v_mul_f32_e32 v128, s101, v128
	v_rndne_f32_e32 v128, v128
	v_cvt_f16_f32_e32 v133, v128
	v_add_f32_e32 v128, v6, v134
	v_add_f32_e32 v134, 1.0, v129
	v_add_f32_e32 v129, v7, v135
	v_med3_f32 v128, v128, s6, v191
	v_med3_f32 v129, v129, s6, v191
	v_add_f32_e32 v130, v3, v131
	v_mul_f32_e32 v128, s100, v128
	v_med3_f32 v130, v130, s6, v191
	v_mul_f32_e32 v129, s100, v129
	v_exp_f32_e32 v128, v128
	v_exp_f32_e32 v129, v129
	v_mul_f32_e32 v130, s100, v130
	v_exp_f32_e32 v130, v130
	v_pk_add_f32 v[128:129], v[128:129], 1.0 op_sel_hi:[1,0]
	v_add_f32_e32 v135, 1.0, v130
	v_mul_f32_e32 v130, v128, v134
	v_rcp_f32_e32 v130, v130
	s_nop 0
	v_mul_f32_e32 v131, v134, v130
	v_mul_f32_e32 v131, s101, v131
	v_rndne_f32_e32 v131, v131
	v_cvt_f16_f32_e32 v134, v131
	v_mul_f32_e32 v131, v129, v135
	v_rcp_f32_e32 v131, v131
	s_nop 0
	v_pk_mul_f32 v[128:129], v[128:129], v[130:131]
	s_nop 0
	v_pk_mul_f32 v[128:129], v[128:129], v[154:155]
	v_mov_b32_e32 v155, v164
	v_cvt_pk_f16_f32 v128, v128, v129
	v_mul_f32_e32 v129, v135, v131
	v_mul_f32_e32 v129, s101, v129
	v_rndne_f32_e32 v129, v129
	v_cvt_f16_f32_e32 v129, v129
	v_pack_b32_f16 v130, v134, v128
	v_ashrrev_i32_e32 v134, 3, v200
	v_bfi_b32 v131, s98, v129, v128
	v_bfi_b32 v129, s98, v133, v132
	v_pack_b32_f16 v128, v147, v132
	v_and_b32_e32 v147, 7, v200
	ds_write_b128 v158, v[128:131] offset:28672
	v_lshlrev_b32_e32 v129, 1, v147
	v_lshl_add_u32 v128, v134, 8, v192
	v_and_b32_e32 v130, 15, v134
	v_bitop3_b32 v131, v129, v134, 15 bitop3:0x78
	v_lshl_or_b32 v131, v131, 4, v128
	v_bitop3_b32 v129, v129, v130, 1 bitop3:0x36
	s_waitcnt lgkmcnt(0)
	s_barrier
	v_lshl_or_b32 v132, v129, 4, v128
	ds_read_b128 v[128:131], v131
	s_waitcnt lgkmcnt(0)
	v_and_b32_e32 v135, 0xffff0000, v129
	v_cvt_f32_f16_e32 v149, v128
	v_cvt_f32_f16_e32 v129, v129
	v_and_b32_e32 v133, 0xffff0000, v131
	v_cvt_f32_f16_e32 v152, v130
	v_cvt_f32_f16_e32 v131, v131
	v_cvt_u32_f32_e32 v149, v149
	v_cvt_u32_f32_e32 v129, v129
	v_cvt_u32_f32_sdwa v152, v152 dst_sel:WORD_1 dst_unused:UNUSED_PAD src0_sel:DWORD
	v_cvt_u32_f32_sdwa v131, v131 dst_sel:BYTE_3 dst_unused:UNUSED_PAD src0_sel:DWORD
	v_or_b32_sdwa v128, v135, v128 dst_sel:DWORD dst_unused:UNUSED_PAD src0_sel:DWORD src1_sel:WORD_1
	v_lshl_or_b32 v129, v129, 8, v149
	v_or3_b32 v152, v129, v152, v131
	v_or_b32_sdwa v129, v133, v130 dst_sel:DWORD dst_unused:UNUSED_PAD src0_sel:DWORD src1_sel:WORD_1
	ds_read_b128 v[130:133], v132
	s_waitcnt lgkmcnt(0)
	v_and_b32_e32 v149, 0xffff0000, v131
	v_cvt_f32_f16_e32 v153, v130
	v_cvt_f32_f16_e32 v131, v131
	v_and_b32_e32 v135, 0xffff0000, v133
	v_cvt_f32_f16_e32 v154, v132
	v_cvt_f32_f16_e32 v133, v133
	v_cvt_u32_f32_e32 v153, v153
	v_cvt_u32_f32_e32 v131, v131
	v_cvt_u32_f32_sdwa v154, v154 dst_sel:WORD_1 dst_unused:UNUSED_PAD src0_sel:DWORD
	v_cvt_u32_f32_sdwa v133, v133 dst_sel:BYTE_3 dst_unused:UNUSED_PAD src0_sel:DWORD
	v_or_b32_sdwa v130, v149, v130 dst_sel:DWORD dst_unused:UNUSED_PAD src0_sel:DWORD src1_sel:WORD_1
	v_lshl_or_b32 v131, v131, 8, v153
	v_or3_b32 v153, v131, v154, v133
	v_or_b32_sdwa v131, v135, v132 dst_sel:DWORD dst_unused:UNUSED_PAD src0_sel:DWORD src1_sel:WORD_1
	v_ashrrev_i32_e32 v135, 31, v134
	v_lshlrev_b64 v[132:133], 10, v[134:135]
	v_lshl_add_u64 v[132:133], s[12:13], 0, v[132:133]
	v_lshlrev_b32_e32 v154, 3, v147
	v_lshl_add_u64 v[132:133], v[132:133], 0, v[154:155]
	global_store_dwordx2 v[132:133], v[152:153], off offset:64
	v_lshlrev_b32_e32 v132, 4, v147
	v_lshl_or_b32 v132, v134, 11, v132
	buffer_store_dwordx4 v[128:131], v132, s[8:11], 0 offen offset:128 sc1
	s_nop 1
	v_add_u32_e32 v128, v197, v199
	ds_read_b128 v[128:131], v128
	s_waitcnt lgkmcnt(0)
	v_and_b32_e32 v133, 0xffff0000, v129
	v_cvt_f32_f16_e32 v134, v128
	v_cvt_f32_f16_e32 v129, v129
	v_and_b32_e32 v132, 0xffff0000, v131
	v_cvt_f32_f16_e32 v135, v130
	v_cvt_f32_f16_e32 v131, v131
	v_cvt_u32_f32_e32 v134, v134
	v_cvt_u32_f32_e32 v129, v129
	v_cvt_u32_f32_sdwa v135, v135 dst_sel:WORD_1 dst_unused:UNUSED_PAD src0_sel:DWORD
	v_cvt_u32_f32_sdwa v131, v131 dst_sel:BYTE_3 dst_unused:UNUSED_PAD src0_sel:DWORD
	v_or_b32_sdwa v128, v133, v128 dst_sel:DWORD dst_unused:UNUSED_PAD src0_sel:DWORD src1_sel:WORD_1
	v_lshl_or_b32 v129, v129, 8, v134
	v_or3_b32 v134, v129, v135, v131
	v_or_b32_sdwa v129, v132, v130 dst_sel:DWORD dst_unused:UNUSED_PAD src0_sel:DWORD src1_sel:WORD_1
	v_add_u32_e32 v130, v197, v198
	ds_read_b128 v[130:133], v130
	s_waitcnt lgkmcnt(0)
	v_and_b32_e32 v149, 0xffff0000, v131
	v_cvt_f32_f16_e32 v135, v130
	v_cvt_f32_f16_e32 v131, v131
	v_and_b32_e32 v147, 0xffff0000, v133
	v_cvt_f32_f16_e32 v152, v132
	v_cvt_f32_f16_e32 v133, v133
	v_cvt_u32_f32_e32 v135, v135
	v_cvt_u32_f32_e32 v131, v131
	v_cvt_u32_f32_sdwa v152, v152 dst_sel:WORD_1 dst_unused:UNUSED_PAD src0_sel:DWORD
	v_cvt_u32_f32_sdwa v133, v133 dst_sel:BYTE_3 dst_unused:UNUSED_PAD src0_sel:DWORD
	v_or_b32_sdwa v130, v149, v130 dst_sel:DWORD dst_unused:UNUSED_PAD src0_sel:DWORD src1_sel:WORD_1
	v_lshl_or_b32 v131, v131, 8, v135
	v_or3_b32 v135, v131, v152, v133
	v_or_b32_sdwa v131, v147, v132 dst_sel:DWORD dst_unused:UNUSED_PAD src0_sel:DWORD src1_sel:WORD_1
	global_store_dwordx2 v[150:151], v[134:135], off offset:64
	buffer_store_dwordx4 v[128:131], v196, s[8:11], 0 offen offset:128 sc1
	s_and_saveexec_b64 s[4:5], vcc
	s_xor_b64 s[4:5], exec, s[4:5]
	s_cbranch_execz .LBB0_465
	v_lshl_add_u32 v129, v148, 8, v192
	v_bitop3_b32 v128, v148, v160, 15 bitop3:0x6c
	v_lshl_or_b32 v130, v128, 4, v129
	v_or_b32_e32 v128, 1, v160
	v_bitop3_b32 v131, v148, v128, 15 bitop3:0x6c
	v_lshl_or_b32 v129, v131, 4, v129
	ds_read_b128 v[130:133], v130
	v_ashrrev_i32_e32 v149, 31, v148
	v_mov_b32_e32 v141, v164
	v_ashrrev_i32_e32 v147, 31, v146
	v_ashrrev_i32_e32 v145, 31, v144
	s_waitcnt lgkmcnt(0)
	v_and_b32_e32 v135, 0xffff0000, v131
	v_cvt_f32_f16_e32 v136, v130
	v_cvt_f32_f16_e32 v131, v131
	v_and_b32_e32 v134, 0xffff0000, v133
	v_cvt_f32_f16_e32 v137, v132
	v_cvt_f32_f16_e32 v133, v133
	v_cvt_u32_f32_e32 v136, v136
	v_cvt_u32_f32_e32 v131, v131
	v_cvt_u32_f32_sdwa v137, v137 dst_sel:WORD_1 dst_unused:UNUSED_PAD src0_sel:DWORD
	v_cvt_u32_f32_sdwa v133, v133 dst_sel:BYTE_3 dst_unused:UNUSED_PAD src0_sel:DWORD
	v_or_b32_sdwa v130, v135, v130 dst_sel:DWORD dst_unused:UNUSED_PAD src0_sel:DWORD src1_sel:WORD_1
	v_lshl_or_b32 v131, v131, 8, v136
	v_ashrrev_i32_e32 v143, 31, v142
	v_or3_b32 v136, v131, v137, v133
	v_or_b32_sdwa v131, v134, v132 dst_sel:DWORD dst_unused:UNUSED_PAD src0_sel:DWORD src1_sel:WORD_1
	ds_read_b128 v[132:135], v129
	s_waitcnt lgkmcnt(0)
	v_and_b32_e32 v138, 0xffff0000, v133
	v_cvt_f32_f16_e32 v137, v132
	v_cvt_f32_f16_e32 v133, v133
	v_and_b32_e32 v129, 0xffff0000, v135
	v_cvt_f32_f16_e32 v139, v134
	v_cvt_f32_f16_e32 v135, v135
	v_cvt_u32_f32_e32 v137, v137
	v_cvt_u32_f32_e32 v133, v133
	v_cvt_u32_f32_sdwa v139, v139 dst_sel:WORD_1 dst_unused:UNUSED_PAD src0_sel:DWORD
	v_cvt_u32_f32_sdwa v135, v135 dst_sel:BYTE_3 dst_unused:UNUSED_PAD src0_sel:DWORD
	v_or_b32_sdwa v132, v138, v132 dst_sel:DWORD dst_unused:UNUSED_PAD src0_sel:DWORD src1_sel:WORD_1
	v_lshl_or_b32 v133, v133, 8, v137
	v_or3_b32 v137, v133, v139, v135
	v_or_b32_sdwa v133, v129, v134 dst_sel:DWORD dst_unused:UNUSED_PAD src0_sel:DWORD src1_sel:WORD_1
	v_lshlrev_b64 v[134:135], 10, v[148:149]
	v_lshl_add_u64 v[134:135], s[12:13], 0, v[134:135]
	v_lshl_add_u64 v[134:135], v[134:135], 0, v[140:141]
	v_lshl_or_b32 v129, v148, 11, v159
	global_store_dwordx2 v[134:135], v[136:137], off offset:64
	buffer_store_dwordx4 v[130:133], v129, s[8:11], 0 offen offset:128 sc1
	v_lshl_add_u32 v129, v146, 8, v192
	s_nop 0
	v_bitop3_b32 v130, v146, v160, 15 bitop3:0x6c
	v_lshl_or_b32 v130, v130, 4, v129
	v_bitop3_b32 v131, v146, v128, 15 bitop3:0x6c
	v_lshl_or_b32 v129, v131, 4, v129
	ds_read_b128 v[130:133], v130
	s_waitcnt lgkmcnt(0)
	v_and_b32_e32 v135, 0xffff0000, v131
	v_cvt_f32_f16_e32 v136, v130
	v_cvt_f32_f16_e32 v131, v131
	v_and_b32_e32 v134, 0xffff0000, v133
	v_cvt_f32_f16_e32 v137, v132
	v_cvt_f32_f16_e32 v133, v133
	v_cvt_u32_f32_e32 v136, v136
	v_cvt_u32_f32_e32 v131, v131
	v_cvt_u32_f32_sdwa v137, v137 dst_sel:WORD_1 dst_unused:UNUSED_PAD src0_sel:DWORD
	v_cvt_u32_f32_sdwa v133, v133 dst_sel:BYTE_3 dst_unused:UNUSED_PAD src0_sel:DWORD
	v_or_b32_sdwa v130, v135, v130 dst_sel:DWORD dst_unused:UNUSED_PAD src0_sel:DWORD src1_sel:WORD_1
	v_lshl_or_b32 v131, v131, 8, v136
	v_or3_b32 v136, v131, v137, v133
	v_or_b32_sdwa v131, v134, v132 dst_sel:DWORD dst_unused:UNUSED_PAD src0_sel:DWORD src1_sel:WORD_1
	ds_read_b128 v[132:135], v129
	s_waitcnt lgkmcnt(0)
	v_and_b32_e32 v138, 0xffff0000, v133
	v_cvt_f32_f16_e32 v137, v132
	v_cvt_f32_f16_e32 v133, v133
	v_and_b32_e32 v129, 0xffff0000, v135
	v_cvt_f32_f16_e32 v139, v134
	v_cvt_f32_f16_e32 v135, v135
	v_cvt_u32_f32_e32 v137, v137
	v_cvt_u32_f32_e32 v133, v133
	v_cvt_u32_f32_sdwa v139, v139 dst_sel:WORD_1 dst_unused:UNUSED_PAD src0_sel:DWORD
	v_cvt_u32_f32_sdwa v135, v135 dst_sel:BYTE_3 dst_unused:UNUSED_PAD src0_sel:DWORD
	v_or_b32_sdwa v132, v138, v132 dst_sel:DWORD dst_unused:UNUSED_PAD src0_sel:DWORD src1_sel:WORD_1
	v_lshl_or_b32 v133, v133, 8, v137
	v_or3_b32 v137, v133, v139, v135
	v_or_b32_sdwa v133, v129, v134 dst_sel:DWORD dst_unused:UNUSED_PAD src0_sel:DWORD src1_sel:WORD_1
	v_lshlrev_b64 v[134:135], 10, v[146:147]
	v_lshl_add_u64 v[134:135], s[12:13], 0, v[134:135]
	v_lshl_add_u64 v[134:135], v[134:135], 0, v[140:141]
	v_lshl_or_b32 v129, v146, 11, v159
	global_store_dwordx2 v[134:135], v[136:137], off offset:64
	buffer_store_dwordx4 v[130:133], v129, s[8:11], 0 offen offset:128 sc1
	v_lshl_add_u32 v129, v144, 8, v192
	s_nop 0
	v_bitop3_b32 v130, v144, v160, 15 bitop3:0x6c
	v_lshl_or_b32 v130, v130, 4, v129
	v_bitop3_b32 v131, v144, v128, 15 bitop3:0x6c
	v_lshl_or_b32 v129, v131, 4, v129
	ds_read_b128 v[130:133], v130
	v_bitop3_b32 v128, v142, v128, 15 bitop3:0x6c
	s_waitcnt lgkmcnt(0)
	v_and_b32_e32 v135, 0xffff0000, v131
	v_cvt_f32_f16_e32 v136, v130
	v_cvt_f32_f16_e32 v131, v131
	v_and_b32_e32 v134, 0xffff0000, v133
	v_cvt_f32_f16_e32 v137, v132
	v_cvt_f32_f16_e32 v133, v133
	v_cvt_u32_f32_e32 v136, v136
	v_cvt_u32_f32_e32 v131, v131
	v_cvt_u32_f32_sdwa v137, v137 dst_sel:WORD_1 dst_unused:UNUSED_PAD src0_sel:DWORD
	v_cvt_u32_f32_sdwa v133, v133 dst_sel:BYTE_3 dst_unused:UNUSED_PAD src0_sel:DWORD
	v_or_b32_sdwa v130, v135, v130 dst_sel:DWORD dst_unused:UNUSED_PAD src0_sel:DWORD src1_sel:WORD_1
	v_lshl_or_b32 v131, v131, 8, v136
	v_or3_b32 v136, v131, v137, v133
	v_or_b32_sdwa v131, v134, v132 dst_sel:DWORD dst_unused:UNUSED_PAD src0_sel:DWORD src1_sel:WORD_1
	ds_read_b128 v[132:135], v129
	s_waitcnt lgkmcnt(0)
	v_and_b32_e32 v138, 0xffff0000, v133
	v_cvt_f32_f16_e32 v137, v132
	v_cvt_f32_f16_e32 v133, v133
	v_and_b32_e32 v129, 0xffff0000, v135
	v_cvt_f32_f16_e32 v139, v134
	v_cvt_f32_f16_e32 v135, v135
	v_cvt_u32_f32_e32 v137, v137
	v_cvt_u32_f32_e32 v133, v133
	v_cvt_u32_f32_sdwa v139, v139 dst_sel:WORD_1 dst_unused:UNUSED_PAD src0_sel:DWORD
	v_cvt_u32_f32_sdwa v135, v135 dst_sel:BYTE_3 dst_unused:UNUSED_PAD src0_sel:DWORD
	v_or_b32_sdwa v132, v138, v132 dst_sel:DWORD dst_unused:UNUSED_PAD src0_sel:DWORD src1_sel:WORD_1
	v_lshl_or_b32 v133, v133, 8, v137
	v_or3_b32 v137, v133, v139, v135
	v_or_b32_sdwa v133, v129, v134 dst_sel:DWORD dst_unused:UNUSED_PAD src0_sel:DWORD src1_sel:WORD_1
	v_lshlrev_b64 v[134:135], 10, v[144:145]
	v_lshl_add_u64 v[134:135], s[12:13], 0, v[134:135]
	v_lshl_add_u64 v[134:135], v[134:135], 0, v[140:141]
	v_lshl_or_b32 v129, v144, 11, v159
	global_store_dwordx2 v[134:135], v[136:137], off offset:64
	buffer_store_dwordx4 v[130:133], v129, s[8:11], 0 offen offset:128 sc1
	v_lshl_add_u32 v129, v142, 8, v192
	s_nop 0
	v_bitop3_b32 v130, v142, v160, 15 bitop3:0x6c
	v_lshl_or_b32 v130, v130, 4, v129
	v_lshl_or_b32 v132, v128, 4, v129
	ds_read_b128 v[128:131], v130
	s_waitcnt lgkmcnt(0)
	v_and_b32_e32 v135, 0xffff0000, v129
	v_cvt_f32_f16_e32 v134, v128
	v_cvt_f32_f16_e32 v129, v129
	v_and_b32_e32 v133, 0xffff0000, v131
	v_cvt_f32_f16_e32 v136, v130
	v_cvt_f32_f16_e32 v131, v131
	v_cvt_u32_f32_e32 v134, v134
	v_cvt_u32_f32_e32 v129, v129
	v_cvt_u32_f32_sdwa v136, v136 dst_sel:WORD_1 dst_unused:UNUSED_PAD src0_sel:DWORD
	v_cvt_u32_f32_sdwa v131, v131 dst_sel:BYTE_3 dst_unused:UNUSED_PAD src0_sel:DWORD
	v_or_b32_sdwa v128, v135, v128 dst_sel:DWORD dst_unused:UNUSED_PAD src0_sel:DWORD src1_sel:WORD_1
	v_lshl_or_b32 v129, v129, 8, v134
	v_or3_b32 v134, v129, v136, v131
	v_or_b32_sdwa v129, v133, v130 dst_sel:DWORD dst_unused:UNUSED_PAD src0_sel:DWORD src1_sel:WORD_1
	ds_read_b128 v[130:133], v132
	s_waitcnt lgkmcnt(0)
	v_and_b32_e32 v137, 0xffff0000, v131
	v_cvt_f32_f16_e32 v135, v130
	v_cvt_f32_f16_e32 v131, v131
	v_and_b32_e32 v136, 0xffff0000, v133
	v_cvt_f32_f16_e32 v138, v132
	v_cvt_f32_f16_e32 v133, v133
	v_cvt_u32_f32_e32 v135, v135
	v_cvt_u32_f32_e32 v131, v131
	v_cvt_u32_f32_sdwa v138, v138 dst_sel:WORD_1 dst_unused:UNUSED_PAD src0_sel:DWORD
	v_cvt_u32_f32_sdwa v133, v133 dst_sel:BYTE_3 dst_unused:UNUSED_PAD src0_sel:DWORD
	v_or_b32_sdwa v130, v137, v130 dst_sel:DWORD dst_unused:UNUSED_PAD src0_sel:DWORD src1_sel:WORD_1
	v_lshl_or_b32 v131, v131, 8, v135
	v_or3_b32 v135, v131, v138, v133
	v_or_b32_sdwa v131, v136, v132 dst_sel:DWORD dst_unused:UNUSED_PAD src0_sel:DWORD src1_sel:WORD_1
	v_lshlrev_b64 v[132:133], 10, v[142:143]
	v_lshl_add_u64 v[132:133], s[12:13], 0, v[132:133]
	v_lshl_add_u64 v[132:133], v[132:133], 0, v[140:141]
	global_store_dwordx2 v[132:133], v[134:135], off offset:64
	v_lshl_or_b32 v132, v142, 11, v159
	buffer_store_dwordx4 v[128:131], v132, s[8:11], 0 offen offset:128 sc1

; __global__ void __launch_bounds__(512) fwd_megakernel(Params p_unused) {
	.amdhsa_kernel _Z14fwd_megakernel6Params
		.amdhsa_group_segment_fixed_size 139264
		.amdhsa_private_segment_fixed_size 0
		.amdhsa_kernarg_size 456
		.amdhsa_user_sgpr_count 2
		.amdhsa_user_sgpr_dispatch_ptr 0
		.amdhsa_user_sgpr_queue_ptr 0
		.amdhsa_user_sgpr_kernarg_segment_ptr 1
		.amdhsa_user_sgpr_dispatch_id 0
		.amdhsa_user_sgpr_kernarg_preload_length 0
		.amdhsa_user_sgpr_kernarg_preload_offset 0
		.amdhsa_user_sgpr_private_segment_size 0
		.amdhsa_uses_dynamic_stack 0
		.amdhsa_enable_private_segment 0
		.amdhsa_system_sgpr_workgroup_id_x 1
		.amdhsa_system_sgpr_workgroup_id_y 0
		.amdhsa_system_sgpr_workgroup_id_z 0
		.amdhsa_system_sgpr_workgroup_info 0
		.amdhsa_system_vgpr_workitem_id 2
		.amdhsa_next_free_vgpr 256
		.amdhsa_next_free_sgpr 102
		.amdhsa_accum_offset 256
		.amdhsa_reserve_vcc 1
		.amdhsa_float_round_mode_32 0
		.amdhsa_float_round_mode_16_64 0
		.amdhsa_float_denorm_mode_32 3
		.amdhsa_float_denorm_mode_16_64 3
		.amdhsa_dx10_clamp 1
		.amdhsa_ieee_mode 1
		.amdhsa_fp16_overflow 0
		.amdhsa_tg_split 0
		.amdhsa_exception_fp_ieee_invalid_op 0
		.amdhsa_exception_fp_denorm_src 0
		.amdhsa_exception_fp_ieee_div_zero 0
		.amdhsa_exception_fp_ieee_overflow 0
		.amdhsa_exception_fp_ieee_underflow 0
		.amdhsa_exception_fp_ieee_inexact 0
		.amdhsa_exception_int_div_zero 0
	.end_amdhsa_kernel

; __global__ void __launch_bounds__(512) fwd_megakernel(Params p_unused) {
amdhsa.kernels:
  - .agpr_count:     0
    .args:
      - .offset:         0
        .size:           200
        .value_kind:     by_value
      - .offset:         200
        .size:           4
        .value_kind:     hidden_block_count_x
      - .offset:         204
        .size:           4
        .value_kind:     hidden_block_count_y
      - .offset:         208
        .size:           4
        .value_kind:     hidden_block_count_z
      - .offset:         212
        .size:           2
        .value_kind:     hidden_group_size_x
      - .offset:         214
        .size:           2
        .value_kind:     hidden_group_size_y
      - .offset:         216
        .size:           2
        .value_kind:     hidden_group_size_z
      - .offset:         218
        .size:           2
        .value_kind:     hidden_remainder_x
      - .offset:         220
        .size:           2
        .value_kind:     hidden_remainder_y
      - .offset:         222
        .size:           2
        .value_kind:     hidden_remainder_z
      - .offset:         240
        .size:           8
        .value_kind:     hidden_global_offset_x
      - .offset:         248
        .size:           8
        .value_kind:     hidden_global_offset_y
      - .offset:         256
        .size:           8
        .value_kind:     hidden_global_offset_z
      - .offset:         264
        .size:           2
        .value_kind:     hidden_grid_dims
      - .offset:         288
        .size:           8
        .value_kind:     hidden_multigrid_sync_arg
    .group_segment_fixed_size: 139264
    .kernarg_segment_align: 8
    .kernarg_segment_size: 456
    .language:       OpenCL C
    .language_version:
      - 2
      - 0
    .max_flat_workgroup_size: 512
    .name:           _Z14fwd_megakernel6Params
    .private_segment_fixed_size: 0
    .sgpr_count:     108
    .sgpr_spill_count: 125
    .symbol:         _Z14fwd_megakernel6Params.kd
    .uniform_work_group_size: 1
    .uses_dynamic_stack: false
    .vgpr_count:     256
    .vgpr_spill_count: 0
    .wavefront_size: 64
